# attention: output-gate values loaded in the item prologue into spare registers (epilogue has no loads or counted waits); cache touches removed
# baseline (speedup 1.0000x reference)
; __device__ __forceinline__ int otid() { int t = threadIdx.x; asm volatile("" : "+v"(t)); return t; }
; __device__ __forceinline__ void item_attn(const Params& p, int l, int aidx) {
;   const int tid = otid(), wid = __builtin_amdgcn_readfirstlane(tid >> 6), lane = tid & 63, fr = lane & 15, fq = lane >> 4;
;   const bool samp = aidx >= 2048;
;   int b, hd, nq, qpos0, ntiles; long tokq0;
;   const float *kbase, *vbase, *kcache = nullptr, *vcache = nullptr;
;   if (!samp) {
;     int qb = 7 - (aidx >> 8); int r = aidx & 255; b = r >> 3; hd = r & 7;
;     nq = 256; qpos0 = qb * 256; tokq0 = (long)b * 2048 + qpos0; ntiles = qb * 4 + 4;
;     kbase = p.out + OFF_KP + ((long)l * 65536 + (long)b * 2048) * 512 + hd * 64;
;     vbase = p.out + OFF_VP + ((long)l * 65536 + (long)b * 2048) * 512 + hd * 64;
;   } else {
;     int r = aidx - 2048; b = r >> 3; hd = r & 7;
;     nq = 16; qpos0 = 1024; tokq0 = NP + (long)b * 16; ntiles = 17;
;     kbase = p.out + OFF_KS + ((long)l * 256 + (long)b * 16) * 512 + hd * 64;
;     vbase = p.out + OFF_VS + ((long)l * 256 + (long)b * 16) * 512 + hd * 64;
;     kcache = p.ck + ((long)(l * 16 + b) * 1024) * 512 + hd * 64;
;     vcache = p.cv + ((long)(l * 16 + b) * 1024) * 512 + hd * 64;
;   }
;   u16* Ks = reinterpret_cast<u16*>(smem + AKS);
;   u16* VT = reinterpret_cast<u16*>(smem + AVT);
;   bf16x8 qf[2][2];
;   bool rowv[2];
; #pragma unroll
;   for (int n = 0; n < 2; ++n) {
;     int row = 32 * wid + 16 * n + fr;
;     rowv[n] = row < nq;
; #pragma unroll
;     for (int ks = 0; ks < 2; ++ks) {
;       bf16x8 z = {0, 0, 0, 0, 0, 0, 0, 0};
;       if (rowv[n]) z = *reinterpret_cast<const bf16x8*>(p.sq + (tokq0 + row) * 512 + hd * 64 + ks * 32 + fq * 8);
;       qf[n][ks] = z;
;     }
;   }
.LBB0_509:
	v_xor_b32_e32 v252, 16, v215
	v_xor_b32_e32 v253, 32, v215
	v_xor_b32_e32 v254, 48, v215
	v_lshlrev_b32_e32 v252, 2, v252
	v_lshlrev_b32_e32 v253, 2, v253
	v_lshlrev_b32_e32 v254, 2, v254
	s_ashr_i32 s2, s2, 6
	v_and_b32_e32 v33, 15, v32
	s_lshl_b32 s21, s2, 5
	v_readlane_b32 s48, v247, 7
	v_or_b32_e32 v84, s21, v33
	s_lshl_b64 s[44:45], s[28:29], 1
	v_readlane_b32 s52, v247, 11
	v_readlane_b32 s53, v247, 12
	s_add_u32 s0, s52, s44
	v_ashrrev_i32_e32 v85, 31, v84
	s_addc_u32 s1, s53, s45
	v_and_b32_e32 v190, 48, v32
	v_lshl_add_u64 v[0:1], s[34:35], 0, v[84:85]
	v_lshl_add_u64 v[8:9], s[0:1], 0, v[190:191]
	v_lshlrev_b64 v[82:83], 10, v[0:1]
	v_cmp_gt_i32_e64 s[8:9], s47, v84
	v_lshl_add_u64 v[10:11], v[8:9], 0, v[82:83]
	v_mov_b32_e32 v0, 0
	v_mov_b32_e32 v4, 0
	v_mov_b32_e32 v5, 0
	v_mov_b32_e32 v6, 0
	v_mov_b32_e32 v7, 0
	v_readlane_b32 s49, v247, 8
	v_readlane_b32 s50, v247, 9
	v_readlane_b32 s51, v247, 10
	v_readlane_b32 s54, v247, 13
	v_readlane_b32 s55, v247, 14
	v_readlane_b32 s56, v247, 15
	v_readlane_b32 s57, v247, 16
	v_readlane_b32 s58, v247, 17
	v_readlane_b32 s59, v247, 18
	v_readlane_b32 s60, v247, 19
	v_readlane_b32 s61, v247, 20
	v_readlane_b32 s62, v247, 21
	v_readlane_b32 s63, v247, 22
	s_and_saveexec_b64 s[0:1], s[8:9]
	s_cbranch_execz .LBB0_511
	global_load_dwordx4 v[4:7], v[10:11], off

; __device__ __forceinline__ void item_attn(const Params& p, int l, int aidx) {
;     ...
;   const bool wave_has_rows = (32 * wid) < nq;
;   f32x4 oacc[4][2];
; #pragma unroll
;   for (int md = 0; md < 4; ++md)
; #pragma unroll
;     for (int n = 0; n < 2; ++n) oacc[md][n] = f32x4{0.f, 0.f, 0.f, 0.f};
;   float carry[2] = {1.f, 1.f};
;   const int wave_qmax = qpos0 + 32 * wid + 31;
;   float4 kreg[2][2]; float vreg[2][8];
;     ...
;     uint2 gz[2][4];
; #pragma unroll
;     for (int n = 0; n < 2; ++n) {
;       int row = 32 * wid + 16 * n + fr; if (row >= nq) row = nq - 1;
; #pragma unroll
;       for (int md = 0; md < 4; ++md) gz[n][md] = *reinterpret_cast<const uint2*>(p.gzc + (tokq0 + row) * 512 + hd * 64 + md * 16 + fq * 4);
;     }
.LBB0_625:
	global_load_dword v126, v102, s[0:1]
	s_cmp_ge_i32 s21, s47
	s_cselect_b64 s[0:1], -1, 0
	s_lshl_b32 s2, s48, 1
	s_addk_i32 s2, 0x100
	v_bfe_u32 v32, v32, 4, 2
	v_mov_b32_e32 v38, s2
	s_movk_i32 s2, 0x90
	v_mad_u32_u24 v115, v35, s2, v38
	v_xor_b32_e32 v35, 1, v32
	v_cmp_gt_u32_e64 s[14:15], v35, v32
	v_xor_b32_e32 v35, 2, v32
	v_lshlrev_b32_e32 v36, 3, v32
	v_or_b32_e32 v37, s20, v33
	v_cmp_gt_u32_e64 s[16:17], v35, v32
	v_xor_b32_e32 v35, 3, v32
	s_add_i32 s52, s18, -1
	v_lshl_add_u32 v34, v34, 1, v216
	v_lshlrev_b32_e32 v114, 2, v32
	v_cmp_gt_u32_e64 s[18:19], v35, v32
	v_add_u32_e32 v85, s21, v37
	v_mul_lo_u32 v32, v87, s2
	v_mul_lo_u32 v35, v89, s2
	v_mul_u32_u24_e32 v33, 0x90, v33
	v_lshlrev_b32_e32 v37, 1, v36
	s_movk_i32 s2, 0x100
	v_mov_b32_e32 v60, v191
	v_mov_b32_e32 v61, v191
	s_add_i32 s50, s20, s21
	v_add3_u32 v118, s2, v33, v37
	v_sub_u32_e32 v119, 0, v36
	v_mov_b32_e32 v199, v198
	v_mov_b32_e32 v62, v191
	v_mov_b32_e32 v63, v191
	v_add_u32_e32 v120, v34, v32
	v_add_u32_e32 v121, v34, v35
	v_mov_b64_e32 v[44:45], v[60:61]
	v_mov_b64_e32 v[56:57], v[60:61]
	v_mov_b64_e32 v[36:37], v[60:61]
	v_mov_b64_e32 v[52:53], v[60:61]
	v_mov_b64_e32 v[40:41], v[60:61]
	v_mov_b64_e32 v[48:49], v[60:61]
	v_mov_b64_e32 v[32:33], v[60:61]
	s_or_b32 s51, s50, 31
	v_add_u32_e32 v88, s20, v86
	v_sub_u32_e32 v116, 0x40f, v87
	v_sub_u32_e32 v117, 0x40f, v89
	v_mov_b64_e32 v[46:47], v[62:63]
	v_mov_b64_e32 v[58:59], v[62:63]
	v_mov_b64_e32 v[38:39], v[62:63]
	v_mov_b64_e32 v[54:55], v[62:63]
	v_mov_b64_e32 v[42:43], v[62:63]
	v_mov_b64_e32 v[50:51], v[62:63]
	v_mov_b64_e32 v[34:35], v[62:63]
	v_mov_b64_e32 v[90:91], v[198:199]
	s_add_i32 s99, s47, -1
	v_readlane_b32 s100, v247, 13
	v_readlane_b32 s101, v247, 14
	v_min_i32_e32 v238, s99, v84
	v_lshlrev_b32_e32 v240, 1, v114
	v_mov_b32_e32 v241, 0
	s_add_u32 s100, s100, s44
	s_addc_u32 s101, s101, s45
	v_ashrrev_i32_e32 v239, 31, v238
	v_min_i32_e32 v242, s99, v86
	v_lshl_add_u64 v[238:239], s[34:35], 0, v[238:239]
	v_ashrrev_i32_e32 v243, 31, v242
	v_lshlrev_b64 v[238:239], 10, v[238:239]
	v_lshl_add_u64 v[242:243], s[34:35], 0, v[242:243]
	v_lshl_add_u64 v[238:239], s[100:101], 0, v[238:239]
	v_lshlrev_b64 v[242:243], 10, v[242:243]
	v_lshl_add_u64 v[238:239], v[238:239], 0, v[240:241]
	v_lshl_add_u64 v[242:243], s[100:101], 0, v[242:243]
	global_load_dwordx2 v[230:231], v[238:239], off
	global_load_dwordx2 v[232:233], v[238:239], off offset:32
	global_load_dwordx2 v[234:235], v[238:239], off offset:64
	global_load_dwordx2 v[236:237], v[238:239], off offset:96
	v_lshl_add_u64 v[242:243], v[242:243], 0, v[240:241]
	s_nop 1
	global_load_dword v229, v[242:243], off offset:96
	global_load_dword v244, v[242:243], off offset:100
	global_load_dwordx2 v[238:239], v[242:243], off
	global_load_dwordx2 v[240:241], v[242:243], off offset:32
	global_load_dwordx2 v[242:243], v[242:243], off offset:64
	s_branch .LBB0_629

; __device__ __forceinline__ float fexp(float x) { return __builtin_amdgcn_exp2f(x * 1.44269504f); }
; __device__ __forceinline__ void item_attn(const Params& p, int l, int aidx) {
;     ...
;     if (!wave_done && kt * 64 < wave_qmax) {
;       f32x4 z[4][2];
; #pragma unroll
;       for (int m = 0; m < 4; ++m) {
;         bf16x8 a0 = *reinterpret_cast<const bf16x8*>(Ks + (m * 16 + fr) * 72 + fq * 8);
;         bf16x8 a1 = *reinterpret_cast<const bf16x8*>(Ks + (m * 16 + fr) * 72 + 32 + fq * 8);
; #pragma unroll
;         for (int n = 0; n < 2; ++n) {
;           f32x4 zz = f32x4{0.f, 0.f, 0.f, 0.f};
;           zz = __builtin_amdgcn_mfma_f32_16x16x32_bf16(a0, qf[n][0], zz, 0, 0, 0);
;           zz = __builtin_amdgcn_mfma_f32_16x16x32_bf16(a1, qf[n][1], zz, 0, 0, 0);
;           z[m][n] = zz;
;         }
;       }
;       unsigned pk[4][2][2];
;       auto sb_weights = [&](auto MASKED) {
; #pragma unroll
;         for (int n = 0; n < 2; ++n) {
;           const int qpos = qpos0 + 32 * wid + 16 * n + fr;
;           float wgt[4][4], excl[4][4], later[4], TT[4];
; #pragma unroll
;           for (int m = 0; m < 4; ++m) {
;             float f[4];
; #pragma unroll
;             for (int j = 0; j < 4; ++j) {
;               const float e = fexp(fminf(-z[m][n][j], 80.f));
;               const float sg = __builtin_amdgcn_rcpf(1.f + e);
;               if (decltype(MASKED)::value) {
;                 const bool ok = (kt * 64 + m * 16 + fq * 4 + j) < qpos;
;                 wgt[m][j] = ok ? sg : 0.f;
;                 f[j] = ok ? e * sg : 1.f;
;               } else { wgt[m][j] = sg; f[j] = e * sg; }
;             }
;             excl[m][3] = 1.f; excl[m][2] = f[3]; excl[m][1] = f[3] * f[2]; excl[m][0] = excl[m][1] * f[1];
;             const float G = excl[m][0] * f[0];
;             const float g1 = __shfl_xor(G, 16), g2 = __shfl_xor(G, 32), g3 = __shfl_xor(G, 48);
;             later[m] = ((fq ^ 1) > fq ? g1 : 1.f) * ((fq ^ 2) > fq ? g2 : 1.f) * ((fq ^ 3) > fq ? g3 : 1.f);
;             TT[m] = (G * g1) * (g2 * g3);
.LBB0_687:
	s_xor_b64 s[0:1], s[0:1], -1
	s_andn2_b64 vcc, exec, s[0:1]
	s_mov_b64 s[0:1], -1
	s_cbranch_vccnz .LBB0_694
	s_cmp_ge_i32 s24, s51
	s_mov_b64 s[0:1], 0
	s_cbranch_scc1 .LBB0_694
	ds_read_b128 v[64:67], v118
	ds_read_b128 v[68:71], v118 offset:64
	s_mov_b32 s100, 0xbfb8aa3b
	s_nop 0
	s_nop 0
	s_waitcnt lgkmcnt(1)
	v_mfma_f32_16x16x32_bf16 v[72:75], v[64:67], v[4:7], 0
	s_nop 0
	s_add_i32 s0, s49, 0x7f
	s_cmp_ge_i32 s0, s50
	v_mfma_f32_16x16x32_bf16 v[64:67], v[64:67], v[12:15], 0
	s_nop 0
	s_nop 0
	s_nop 0
	s_waitcnt lgkmcnt(0)
	v_mfma_f32_16x16x32_bf16 v[72:75], v[68:71], v[0:3], v[72:75]
	s_nop 0
	s_mov_b64 s[0:1], -1
	v_mfma_f32_16x16x32_bf16 v[64:67], v[68:71], v[8:11], v[64:67]
	ds_read_b128 v[68:71], v118 offset:2304
	ds_read_b128 v[76:79], v118 offset:2368
	s_nop 0
	s_nop 1
	s_nop 0
	s_waitcnt lgkmcnt(1)
	v_mfma_f32_16x16x32_bf16 v[92:95], v[68:71], v[4:7], 0
	v_pk_mul_f32 v[160:161], v[72:73], s[100:101] op_sel_hi:[1,0]
	s_nop 0
	v_pk_mul_f32 v[158:159], v[74:75], s[100:101] op_sel:[1,0] op_sel_hi:[0,0]
	v_mfma_f32_16x16x32_bf16 v[68:71], v[68:71], v[12:15], 0
	s_nop 0
	v_pk_mul_f32 v[144:145], v[64:65], s[100:101] op_sel:[1,0] op_sel_hi:[0,0]
	s_nop 0
	s_waitcnt lgkmcnt(0)
	v_mfma_f32_16x16x32_bf16 v[92:95], v[76:79], v[0:3], v[92:95]
	v_pk_mul_f32 v[142:143], v[66:67], s[100:101] op_sel_hi:[1,0]
	v_mfma_f32_16x16x32_bf16 v[68:71], v[76:79], v[8:11], v[68:71]
	ds_read_b128 v[76:79], v118 offset:4608
	ds_read_b128 v[96:99], v118 offset:4672
	s_nop 3
	s_nop 0
	v_pk_mul_f32 v[156:157], v[92:93], s[100:101] op_sel:[1,0] op_sel_hi:[0,0]
	s_waitcnt lgkmcnt(1)
	v_mfma_f32_16x16x32_bf16 v[128:131], v[76:79], v[4:7], 0
	s_nop 0
	v_pk_mul_f32 v[154:155], v[94:95], s[100:101] op_sel_hi:[1,0]
	v_mfma_f32_16x16x32_bf16 v[76:79], v[76:79], v[12:15], 0
	s_waitcnt lgkmcnt(0)
	v_mfma_f32_16x16x32_bf16 v[130:133], v[96:99], v[0:3], v[128:131]
	v_mfma_f32_16x16x32_bf16 v[76:79], v[96:99], v[8:11], v[76:79]
	ds_read_b128 v[96:99], v118 offset:6912
	ds_read_b128 v[134:137], v118 offset:6976
	s_nop 0
	s_nop 0
	s_waitcnt lgkmcnt(1)
	v_mfma_f32_16x16x32_bf16 v[138:141], v[96:99], v[4:7], 0
	s_nop 0
	v_mul_f32_e32 v151, s100, v130
	v_mul_f32_e32 v153, s100, v131
	v_mfma_f32_16x16x32_bf16 v[96:99], v[96:99], v[12:15], 0
	s_nop 0
	s_nop 0
	v_mul_f32_e32 v152, s100, v132
	s_waitcnt lgkmcnt(0)
	v_mfma_f32_16x16x32_bf16 v[138:141], v[134:137], v[0:3], v[138:141]
	v_mul_f32_e32 v150, s100, v133
	v_mfma_f32_16x16x32_bf16 v[96:99], v[134:137], v[8:11], v[96:99]
	s_nop 0
	s_nop 4
	v_mul_f32_e32 v147, s100, v138
	v_mul_f32_e32 v149, s100, v139
	v_mul_f32_e32 v148, s100, v140
	v_mul_f32_e32 v146, s100, v141
	s_nop 0
	v_pk_mul_f32 v[140:141], v[68:69], s[100:101] op_sel:[1,0] op_sel_hi:[0,0]
	s_nop 0
	v_pk_mul_f32 v[138:139], v[70:71], s[100:101] op_sel:[1,0] op_sel_hi:[0,0]
	v_pk_mul_f32 v[136:137], v[76:77], s[100:101] op_sel:[1,0] op_sel_hi:[0,0]
	s_nop 0
	v_pk_mul_f32 v[134:135], v[78:79], s[100:101] op_sel:[1,0] op_sel_hi:[0,0]
	s_nop 0
	v_pk_mul_f32 v[132:133], v[96:97], s[100:101] op_sel_hi:[1,0]
	s_nop 0
	v_pk_mul_f32 v[130:131], v[98:99], s[100:101] op_sel:[1,0] op_sel_hi:[0,0]
	s_cbranch_scc0 .LBB0_691
	v_min_f32_e32 v64, 0x42e6d4ca, v160
	v_min_f32_e32 v65, 0x42e6d4ca, v161
	v_exp_f32_e32 v67, v64
	v_exp_f32_e32 v69, v65
	v_min_f32_e32 v65, 0x42e6d4ca, v159
	v_exp_f32_e32 v65, v65
	v_min_f32_e32 v68, 0x42e6d4ca, v157
	v_add_f32_e32 v66, 1.0, v67
	v_rcp_f32_e32 v73, v66
	v_add_f32_e32 v66, 1.0, v69
	v_exp_f32_e32 v68, v68
	v_rcp_f32_e32 v75, v66
	v_add_f32_e32 v66, 1.0, v65
	v_rcp_f32_e32 v77, v66
	v_min_f32_e32 v66, 0x42e6d4ca, v158
	v_min_f32_e32 v70, 0x42e6d4ca, v156
	v_exp_f32_e32 v71, v66
	v_add_f32_e32 v66, 1.0, v68
	v_rcp_f32_e32 v66, v66
	v_exp_f32_e32 v70, v70
	v_add_u32_e32 v64, s49, v114
	v_add_u32_e32 v180, 0x50, v64
	v_cmp_lt_i32_e32 vcc, v180, v85
	v_min_f32_e32 v74, 0x42e6d4ca, v154
	s_nop 0
	v_cndmask_b32_e32 v72, 0, v66, vcc
	v_mul_f32_e32 v66, v68, v66
	v_add_f32_e32 v68, 1.0, v70
	v_rcp_f32_e32 v68, v68
	v_exp_f32_e32 v74, v74
	v_add_u32_e32 v181, 0x51, v64
	v_cndmask_b32_e32 v66, 1.0, v66, vcc
	v_cmp_lt_i32_e32 vcc, v181, v85
	v_min_f32_e32 v78, 0x42e6d4ca, v155
	s_nop 0
	v_cndmask_b32_e32 v76, 0, v68, vcc
	v_mul_f32_e32 v68, v70, v68
	v_add_f32_e32 v70, 1.0, v74
	v_rcp_f32_e32 v70, v70
	v_exp_f32_e32 v78, v78
	v_add_u32_e32 v182, 0x52, v64
	v_cndmask_b32_e32 v68, 1.0, v68, vcc
	v_cmp_lt_i32_e32 vcc, v182, v85
	v_add_u32_e32 v183, 0x53, v64
	v_min_f32_e32 v98, 0x42e6d4ca, v153
	v_cndmask_b32_e32 v92, 0, v70, vcc
	v_mul_f32_e32 v70, v74, v70
	v_add_f32_e32 v74, 1.0, v78
	v_rcp_f32_e32 v74, v74
	v_cndmask_b32_e32 v70, 1.0, v70, vcc
	v_cmp_lt_i32_e32 vcc, v183, v85
	v_exp_f32_e32 v98, v98
	s_nop 0
	v_cndmask_b32_e32 v101, 0, v74, vcc
	v_mul_f32_e32 v74, v78, v74
	v_cndmask_b32_e32 v94, 1.0, v74, vcc
	v_mul_f32_e32 v70, v94, v70
	v_mul_f32_e32 v68, v68, v70
	v_mul_f32_e32 v66, v66, v68
	ds_bpermute_b32 v74, v252, v66
	ds_bpermute_b32 v78, v253, v66
	ds_bpermute_b32 v95, v254, v66
	v_add_u32_e32 v184, 0x60, v64
	v_cmp_lt_i32_e32 vcc, v184, v85
	s_waitcnt lgkmcnt(2)
	v_cndmask_b32_e64 v93, 1.0, v74, s[14:15]
	s_waitcnt lgkmcnt(1)
	v_cndmask_b32_e64 v96, 1.0, v78, s[16:17]
	v_mul_f32_e32 v93, v93, v96
	v_min_f32_e32 v96, 0x42e6d4ca, v151
	v_exp_f32_e32 v96, v96
	s_waitcnt lgkmcnt(0)
; __device__ __forceinline__ float fexp(float x) { return __builtin_amdgcn_exp2f(x * 1.44269504f); }
; __device__ __forceinline__ void item_attn(const Params& p, int l, int aidx) {
;     ...
; #pragma unroll
;           for (int m = 0; m < 4; ++m) {
;             float f[4];
; #pragma unroll
;             for (int j = 0; j < 4; ++j) {
;               const float e = fexp(fminf(-z[m][n][j], 80.f));
;               const float sg = __builtin_amdgcn_rcpf(1.f + e);
;               if (decltype(MASKED)::value) {
;                 const bool ok = (kt * 64 + m * 16 + fq * 4 + j) < qpos;
;                 wgt[m][j] = ok ? sg : 0.f;
;                 f[j] = ok ? e * sg : 1.f;
;               } else { wgt[m][j] = sg; f[j] = e * sg; }
;             }
;             excl[m][3] = 1.f; excl[m][2] = f[3]; excl[m][1] = f[3] * f[2]; excl[m][0] = excl[m][1] * f[1];
;             const float G = excl[m][0] * f[0];
;             const float g1 = __shfl_xor(G, 16), g2 = __shfl_xor(G, 32), g3 = __shfl_xor(G, 48);
;             later[m] = ((fq ^ 1) > fq ? g1 : 1.f) * ((fq ^ 2) > fq ? g2 : 1.f) * ((fq ^ 3) > fq ? g3 : 1.f);
;             TT[m] = (G * g1) * (g2 * g3);
;           }
	v_cndmask_b32_e64 v97, 1.0, v95, s[18:19]
	v_mul_f32_e32 v93, v97, v93
	v_min_f32_e32 v99, 0x42e6d4ca, v152
	v_add_f32_e32 v97, 1.0, v96
	v_rcp_f32_e32 v97, v97
	v_exp_f32_e32 v99, v99
	v_add_u32_e32 v185, 0x61, v64
	v_cndmask_b32_e32 v169, 0, v97, vcc
	v_mul_f32_e32 v96, v96, v97
	v_add_f32_e32 v97, 1.0, v98
	v_rcp_f32_e32 v97, v97
	v_cndmask_b32_e32 v96, 1.0, v96, vcc
	v_cmp_lt_i32_e32 vcc, v185, v85
	v_add_u32_e32 v187, 0x62, v64
	v_mul_f32_e32 v164, v78, v95
	v_cndmask_b32_e32 v186, 0, v97, vcc
	v_mul_f32_e32 v97, v98, v97
	v_add_f32_e32 v98, 1.0, v99
	v_rcp_f32_e32 v100, v98
	v_min_f32_e32 v98, 0x42e6d4ca, v150
	v_exp_f32_e32 v162, v98
	v_cndmask_b32_e32 v97, 1.0, v97, vcc
	v_cmp_lt_i32_e32 vcc, v187, v85
	v_mul_f32_e32 v99, v99, v100
	v_min_f32_e32 v78, 0x42e6d4ca, v147
	v_cndmask_b32_e32 v98, 0, v100, vcc
	v_add_f32_e32 v100, 1.0, v162
	v_rcp_f32_e32 v100, v100
	v_add_u32_e32 v199, 0x63, v64
	v_cndmask_b32_e32 v99, 1.0, v99, vcc
	v_cmp_lt_i32_e32 vcc, v199, v85
	v_exp_f32_e32 v78, v78
	v_add_u32_e32 v203, 0x70, v64
	v_cndmask_b32_e32 v200, 0, v100, vcc
	v_mul_f32_e32 v100, v162, v100
	v_cndmask_b32_e32 v100, 1.0, v100, vcc
	v_mul_f32_e32 v201, v100, v99
	v_min_f32_e32 v99, 0x42e6d4ca, v149
	v_add_f32_e32 v95, 1.0, v78
	v_rcp_f32_e32 v95, v95
	v_exp_f32_e32 v99, v99
	v_cmp_lt_i32_e32 vcc, v203, v85
	v_min_f32_e32 v165, 0x42e6d4ca, v148
	v_mul_f32_e32 v78, v78, v95
	v_cndmask_b32_e32 v204, 0, v95, vcc
	v_add_f32_e32 v95, 1.0, v99
	v_rcp_f32_e32 v95, v95
	v_exp_f32_e32 v165, v165
	v_add_u32_e32 v205, 0x71, v64
	v_cndmask_b32_e32 v78, 1.0, v78, vcc
	v_cmp_lt_i32_e32 vcc, v205, v85
	v_min_f32_e32 v167, 0x42e6d4ca, v146
	s_nop 0
	v_cndmask_b32_e32 v206, 0, v95, vcc
	v_mul_f32_e32 v95, v99, v95
	v_add_f32_e32 v99, 1.0, v165
	v_rcp_f32_e32 v99, v99
	v_exp_f32_e32 v167, v167
	v_add_u32_e32 v207, 0x72, v64
	v_cndmask_b32_e32 v95, 1.0, v95, vcc
	v_cmp_lt_i32_e32 vcc, v207, v85
	v_add_u32_e32 v218, 0x73, v64
	v_add_u32_e32 v178, 64, v64
	v_cndmask_b32_e32 v168, 0, v99, vcc
	v_mul_f32_e32 v99, v165, v99
	v_add_f32_e32 v165, 1.0, v167
	v_rcp_f32_e32 v165, v165
	v_cndmask_b32_e32 v99, 1.0, v99, vcc
	v_cmp_lt_i32_e32 vcc, v218, v85
	v_add_u32_e32 v179, 0x41, v64
	v_mul_f32_e32 v202, v97, v201
	v_cndmask_b32_e32 v64, 0, v165, vcc
	v_mul_f32_e32 v165, v167, v165
	v_cndmask_b32_e32 v170, 1.0, v165, vcc
	v_mul_f32_e32 v97, v96, v202
	v_mul_f32_e32 v219, v170, v99
	ds_bpermute_b32 v163, v252, v97
	ds_bpermute_b32 v96, v253, v97
	v_mul_f32_e32 v220, v95, v219
	ds_bpermute_b32 v166, v254, v97
	v_mul_f32_e32 v172, v78, v220
	ds_bpermute_b32 v173, v253, v172
	ds_bpermute_b32 v174, v252, v172
	ds_bpermute_b32 v175, v254, v172
	v_mul_f32_e32 v162, v66, v74
	s_waitcnt lgkmcnt(5)
	v_cndmask_b32_e64 v66, 1.0, v163, s[14:15]
	s_waitcnt lgkmcnt(4)
	v_cndmask_b32_e64 v74, 1.0, v96, s[16:17]
	v_mul_f32_e32 v66, v66, v74
	s_waitcnt lgkmcnt(3)
	v_cndmask_b32_e64 v74, 1.0, v166, s[18:19]
	v_mul_f32_e32 v99, v74, v66
	s_waitcnt lgkmcnt(2)
	v_cndmask_b32_e64 v66, 1.0, v173, s[16:17]
	s_waitcnt lgkmcnt(0)
	v_pk_mul_f32 v[172:173], v[172:173], v[174:175]
	v_mul_f32_e32 v176, v97, v163
	v_mov_b32_e32 v97, v172
	v_mov_b32_e32 v167, v173
	v_pk_mul_f32 v[96:97], v[96:97], v[166:167]
	v_mov_b32_e32 v177, v91
	v_pk_mul_f32 v[166:167], v[176:177], v[96:97]
	v_cndmask_b32_e64 v74, 1.0, v174, s[14:15]
	v_mov_b32_e32 v163, v166
	v_mov_b32_e32 v165, v167
	v_pk_mul_f32 v[96:97], v[162:163], v[164:165]
	v_mul_f32_e32 v66, v74, v66
	v_mov_b32_e32 v95, v97
	v_cndmask_b32_e64 v74, 1.0, v175, s[18:19]
	v_pk_mul_f32 v[92:93], v[92:93], v[94:95]
	v_mul_f32_e32 v171, v74, v66
	v_mul_f32_e32 v66, v72, v68
	v_mul_f32_e32 v68, v76, v70
	v_mul_f32_e32 v176, v101, v93
	v_mov_b32_e32 v101, v167
	v_mul_f32_e32 v95, v66, v93
	v_mul_f32_e32 v163, v68, v93
	v_mul_f32_e32 v165, v92, v93
	v_mul_f32_e32 v66, v169, v202
	v_mul_f32_e32 v68, v186, v201
	v_pk_mul_f32 v[92:93], v[98:99], v[100:101]
	v_mov_b32_e32 v169, v91
	v_min_f32_e32 v78, 0x42e6d4ca, v141
	v_mul_f32_e32 v99, v66, v93
	v_mul_f32_e32 v101, v68, v93
	v_mul_f32_e32 v186, v92, v93
	v_mul_f32_e32 v200, v200, v93
	v_pk_mul_f32 v[92:93], v[168:169], v[170:171]
	v_mul_f32_e32 v66, v204, v220
	v_mul_f32_e32 v204, v92, v93
	v_exp_f32_e32 v92, v78
	v_min_f32_e32 v98, 0x42e6d4ca, v140
	v_exp_f32_e32 v98, v98
	v_add_f32_e32 v94, 1.0, v92
	v_rcp_f32_e32 v94, v94
	v_cmp_lt_i32_e32 vcc, v180, v88
	v_mul_f32_e32 v68, v206, v219
	v_min_f32_e32 v162, 0x42e6d4ca, v138
	v_cndmask_b32_e32 v206, 0, v94, vcc
	v_mul_f32_e32 v92, v92, v94
	v_min_f32_e32 v94, 0x42e6d4ca, v139
	v_cndmask_b32_e32 v100, 1.0, v92, vcc
	v_add_f32_e32 v92, 1.0, v98
	v_rcp_f32_e32 v92, v92
	v_exp_f32_e32 v94, v94
	v_exp_f32_e32 v162, v162
	v_cmp_lt_i32_e32 vcc, v181, v88
	v_mul_f32_e32 v201, v66, v93
	v_min_f32_e32 v66, 0x42e6d4ca, v145
	v_cndmask_b32_e32 v219, 0, v92, vcc
	v_mul_f32_e32 v92, v98, v92
	v_add_f32_e32 v98, 1.0, v94
	v_rcp_f32_e32 v98, v98
	v_add_f32_e32 v166, 1.0, v162
	v_rcp_f32_e32 v166, v166
	v_cndmask_b32_e32 v164, 1.0, v92, vcc
	v_cmp_lt_i32_e32 vcc, v182, v88
	v_mul_f32_e32 v94, v94, v98
	s_nop 0
	v_cndmask_b32_e32 v92, 0, v98, vcc
	v_cndmask_b32_e32 v98, 1.0, v94, vcc
	v_mul_f32_e32 v94, v162, v166
	v_min_f32_e32 v162, 0x42e6d4ca, v137
	v_cmp_lt_i32_e32 vcc, v183, v88
	v_exp_f32_e32 v162, v162
	v_mul_f32_e32 v202, v68, v93
	v_cndmask_b32_e32 v94, 1.0, v94, vcc
	v_mul_f32_e32 v221, v94, v98
	v_mul_f32_e32 v222, v164, v221
	v_mul_f32_e32 v183, v100, v222
	v_add_f32_e32 v98, 1.0, v162
	v_min_f32_e32 v100, 0x42e6d4ca, v136
	v_rcp_f32_e32 v98, v98
	v_exp_f32_e32 v100, v100
	v_cndmask_b32_e32 v220, 0, v166, vcc
	v_cmp_lt_i32_e32 vcc, v184, v88
	v_min_f32_e32 v164, 0x42e6d4ca, v135
; __device__ __forceinline__ float fexp(float x) { return __builtin_amdgcn_exp2f(x * 1.44269504f); }
; __device__ __forceinline__ unsigned pack2(float a, float b) { unsigned r; asm volatile("v_cvt_pk_bf16_f32 %0, %1, %2" : "=v"(r) : "v"(a), "v"(b)); return r; }
; __device__ __forceinline__ void item_attn(const Params& p, int l, int aidx) {
;     ...
; #pragma unroll
;           for (int m = 0; m < 4; ++m) {
;             float f[4];
; #pragma unroll
;             for (int j = 0; j < 4; ++j) {
;               const float e = fexp(fminf(-z[m][n][j], 80.f));
;               const float sg = __builtin_amdgcn_rcpf(1.f + e);
;               if (decltype(MASKED)::value) {
;                 const bool ok = (kt * 64 + m * 16 + fq * 4 + j) < qpos;
;                 wgt[m][j] = ok ? sg : 0.f;
;                 f[j] = ok ? e * sg : 1.f;
;               } else { wgt[m][j] = sg; f[j] = e * sg; }
;             }
;             excl[m][3] = 1.f; excl[m][2] = f[3]; excl[m][1] = f[3] * f[2]; excl[m][0] = excl[m][1] * f[1];
;             const float G = excl[m][0] * f[0];
;             const float g1 = __shfl_xor(G, 16), g2 = __shfl_xor(G, 32), g3 = __shfl_xor(G, 48);
;             later[m] = ((fq ^ 1) > fq ? g1 : 1.f) * ((fq ^ 2) > fq ? g2 : 1.f) * ((fq ^ 3) > fq ? g3 : 1.f);
;             TT[m] = (G * g1) * (g2 * g3);
;           }
;           float lm[4]; lm[3] = carry[n]; lm[2] = lm[3] * TT[3]; lm[1] = lm[2] * TT[2]; lm[0] = lm[1] * TT[1];
; #pragma unroll
;           for (int m = 0; m < 4; ++m) {
;             const float base = later[m] * lm[m];
;             float pv[4];
; #pragma unroll
;             for (int j = 0; j < 4; ++j) pv[j] = wgt[m][j] * excl[m][j] * base;
;             pk[m][n][0] = pack2(pv[0], pv[1]); pk[m][n][1] = pack2(pv[2], pv[3]);
;           }
;           carry[n] = lm[0] * TT[0];
	s_nop 0
	v_cndmask_b32_e32 v184, 0, v98, vcc
	v_mul_f32_e32 v98, v162, v98
	v_cndmask_b32_e32 v162, 1.0, v98, vcc
	v_add_f32_e32 v98, 1.0, v100
	v_min_f32_e32 v166, 0x42e6d4ca, v134
	v_rcp_f32_e32 v98, v98
	v_exp_f32_e32 v164, v164
	v_exp_f32_e32 v166, v166
	v_cmp_lt_i32_e32 vcc, v185, v88
	v_min_f32_e32 v68, 0x42e6d4ca, v144
	v_exp_f32_e32 v66, v66
	v_cndmask_b32_e32 v185, 0, v98, vcc
	v_mul_f32_e32 v98, v100, v98
	v_add_f32_e32 v100, 1.0, v164
	v_rcp_f32_e32 v100, v100
	v_add_f32_e32 v168, 1.0, v166
	v_rcp_f32_e32 v168, v168
	v_cndmask_b32_e32 v167, 1.0, v98, vcc
	v_cmp_lt_i32_e32 vcc, v187, v88
	v_exp_f32_e32 v68, v68
	s_nop 0
	v_cndmask_b32_e32 v98, 0, v100, vcc
	v_mul_f32_e32 v100, v164, v100
	v_cndmask_b32_e32 v164, 1.0, v100, vcc
	v_mul_f32_e32 v100, v166, v168
	v_min_f32_e32 v166, 0x42e6d4ca, v132
	v_cmp_lt_i32_e32 vcc, v199, v88
	v_exp_f32_e32 v166, v166
	v_mul_f32_e32 v93, v64, v93
	v_cndmask_b32_e32 v100, 1.0, v100, vcc
	v_mul_f32_e32 v199, v100, v164
	v_mul_f32_e32 v223, v167, v199
	v_mul_f32_e32 v224, v162, v223
	v_add_f32_e32 v162, 1.0, v166
	v_min_f32_e32 v164, 0x42e6d4ca, v133
	v_rcp_f32_e32 v162, v162
	v_exp_f32_e32 v164, v164
	v_cndmask_b32_e32 v187, 0, v168, vcc
	v_cmp_lt_i32_e32 vcc, v203, v88
	v_add_f32_e32 v64, 1.0, v66
	v_min_f32_e32 v70, 0x42e6d4ca, v142
	v_cndmask_b32_e32 v203, 0, v162, vcc
	v_mul_f32_e32 v162, v166, v162
	v_min_f32_e32 v166, 0x42e6d4ca, v131
	v_cndmask_b32_e32 v167, 1.0, v162, vcc
	v_add_f32_e32 v162, 1.0, v164
	v_rcp_f32_e32 v72, v64
	v_add_f32_e32 v64, 1.0, v68
	v_rcp_f32_e32 v162, v162
	v_exp_f32_e32 v166, v166
	v_min_f32_e32 v168, 0x42e6d4ca, v130
	v_rcp_f32_e32 v74, v64
	v_min_f32_e32 v64, 0x42e6d4ca, v143
	v_exp_f32_e32 v70, v70
	v_exp_f32_e32 v168, v168
	v_exp_f32_e32 v64, v64
	v_cmp_lt_i32_e32 vcc, v205, v88
	v_add_f32_e32 v76, 1.0, v70
	v_add_f32_e32 v169, 1.0, v168
	v_cndmask_b32_e32 v205, 0, v162, vcc
	v_mul_f32_e32 v162, v164, v162
	v_add_f32_e32 v164, 1.0, v166
	v_rcp_f32_e32 v164, v164
	v_add_f32_e32 v79, 1.0, v71
	v_rcp_f32_e32 v78, v76
	v_add_f32_e32 v76, 1.0, v64
	v_rcp_f32_e32 v169, v169
	v_rcp_f32_e32 v79, v79
	v_rcp_f32_e32 v76, v76
	v_cndmask_b32_e32 v180, 1.0, v162, vcc
	v_cmp_lt_i32_e32 vcc, v207, v88
	v_pk_mul_f32 v[70:71], v[70:71], v[78:79]
	v_pk_mul_f32 v[64:65], v[64:65], v[76:77]
	v_cndmask_b32_e32 v162, 0, v164, vcc
	v_mul_f32_e32 v164, v166, v164
	v_cndmask_b32_e32 v166, 1.0, v164, vcc
	v_cmp_lt_i32_e32 vcc, v218, v88
	v_mul_f32_e32 v164, v168, v169
	v_or_b32_e32 v168, 3, v178
	v_cndmask_b32_e32 v207, 0, v169, vcc
	v_or_b32_e32 v169, 2, v178
	v_cndmask_b32_e32 v164, 1.0, v164, vcc
	v_cmp_lt_i32_e64 s[22:23], v169, v85
	v_cmp_lt_i32_e64 s[24:25], v168, v85
	v_mul_f32_e32 v218, v164, v166
	v_cmp_lt_i32_e64 s[20:21], v179, v85
	v_cndmask_b32_e64 v166, 0, v77, s[22:23]
	v_cndmask_b32_e64 v227, 0, v79, s[24:25]
	v_pk_mul_f32 v[68:69], v[68:69], v[74:75]
	v_cndmask_b32_e64 v71, 1.0, v71, s[24:25]
	v_cmp_lt_i32_e64 s[24:25], v169, v88
	v_cndmask_b32_e64 v169, 1.0, v65, s[22:23]
	v_cmp_lt_i32_e64 s[22:23], v168, v88
	v_cmp_lt_i32_e32 vcc, v178, v85
	v_cndmask_b32_e64 v226, 0, v75, s[20:21]
	v_pk_mul_f32 v[66:67], v[66:67], v[72:73]
	v_cndmask_b32_e64 v69, 1.0, v69, s[20:21]
	v_cmp_lt_i32_e64 s[20:21], v179, v88
	v_cndmask_b32_e64 v70, 1.0, v70, s[24:25]
	v_cndmask_b32_e64 v168, 1.0, v64, s[22:23]
	v_cndmask_b32_e32 v225, 0, v73, vcc
	v_cndmask_b32_e32 v67, 1.0, v67, vcc
	v_cmp_lt_i32_e32 vcc, v178, v88
	v_cndmask_b32_e64 v68, 1.0, v68, s[20:21]
	v_pk_mul_f32 v[170:171], v[70:71], v[168:169]
	v_cndmask_b32_e32 v66, 1.0, v66, vcc
	v_pk_mul_f32 v[172:173], v[68:69], v[170:171]
	v_mul_f32_e32 v228, v180, v218
	v_pk_mul_f32 v[174:175], v[66:67], v[172:173]
	ds_bpermute_b32 v177, v252, v175
	ds_bpermute_b32 v179, v253, v175
	ds_bpermute_b32 v181, v254, v175
	v_pk_mul_f32 v[96:97], v[96:97], v[96:97] op_sel:[0,1] op_sel_hi:[1,0]
	v_mul_f32_e32 v182, v167, v228
	s_waitcnt lgkmcnt(2)
	v_cndmask_b32_e64 v64, 1.0, v177, s[14:15]
	s_waitcnt lgkmcnt(1)
	v_cndmask_b32_e64 v65, 1.0, v179, s[16:17]
	v_mul_f32_e32 v64, v64, v65
	s_waitcnt lgkmcnt(0)
	v_cndmask_b32_e64 v65, 1.0, v181, s[18:19]
	v_mul_f32_e32 v167, v65, v64
	v_pk_mov_b32 v[64:65], v[70:71], v[96:97] op_sel:[1,0]
	v_mul_f32_e32 v66, v225, v173
	v_mul_f32_e32 v67, v226, v171
	v_pk_mul_f32 v[64:65], v[166:167], v[64:65]
	ds_bpermute_b32 v178, v253, v174
	v_mul_f32_e32 v66, v66, v65
	v_mul_f32_e32 v67, v67, v65
	v_mul_f32_e32 v64, v64, v65
	v_mul_f32_e32 v65, v227, v65
	v_cvt_pk_bf16_f32 v68, v66, v67
	v_cvt_pk_bf16_f32 v69, v64, v65
	v_cvt_pk_bf16_f32 v70, v95, v163
	v_cvt_pk_bf16_f32 v71, v165, v176
	ds_bpermute_b32 v176, v252, v174
	ds_bpermute_b32 v180, v254, v174
	ds_bpermute_b32 v75, v252, v183
	ds_bpermute_b32 v77, v253, v183
	ds_bpermute_b32 v79, v254, v183
	v_cndmask_b32_e64 v97, 0, v74, s[20:21]
	s_waitcnt lgkmcnt(4)
	v_cndmask_b32_e64 v73, 1.0, v176, s[14:15]
	v_cndmask_b32_e64 v74, 1.0, v178, s[16:17]
	v_mul_f32_e32 v73, v73, v74
	s_waitcnt lgkmcnt(3)
	v_cndmask_b32_e64 v74, 1.0, v180, s[18:19]
	v_cvt_pk_bf16_f32 v64, v99, v101
	v_cndmask_b32_e64 v101, 0, v76, s[22:23]
	v_mul_f32_e32 v73, v74, v73
	s_waitcnt lgkmcnt(2)
	v_cndmask_b32_e64 v74, 1.0, v75, s[14:15]
	s_waitcnt lgkmcnt(1)
	v_cndmask_b32_e64 v76, 1.0, v77, s[16:17]
	v_mul_f32_e32 v74, v74, v76
	s_waitcnt lgkmcnt(0)
	v_cndmask_b32_e64 v76, 1.0, v79, s[18:19]
	v_cvt_pk_bf16_f32 v65, v186, v200
	v_cvt_pk_bf16_f32 v66, v201, v202
	v_cvt_pk_bf16_f32 v67, v204, v93
	v_mul_f32_e32 v93, v76, v74
	ds_bpermute_b32 v163, v252, v224
	ds_bpermute_b32 v74, v253, v224
	v_cndmask_b32_e32 v95, 0, v72, vcc
	v_cndmask_b32_e64 v72, 0, v78, s[24:25]
	ds_bpermute_b32 v78, v254, v224
	v_pk_mul_f32 v[166:167], v[174:175], v[176:177]
	v_mul_f32_e32 v76, v183, v75
	ds_bpermute_b32 v183, v253, v182
	ds_bpermute_b32 v176, v252, v182
	ds_bpermute_b32 v177, v254, v182
	v_pk_mul_f32 v[174:175], v[178:179], v[180:181]
	s_waitcnt lgkmcnt(5)
; __device__ __forceinline__ float fexp(float x) { return __builtin_amdgcn_exp2f(x * 1.44269504f); }
; __device__ __forceinline__ unsigned pack2(float a, float b) { unsigned r; asm volatile("v_cvt_pk_bf16_f32 %0, %1, %2" : "=v"(r) : "v"(a), "v"(b)); return r; }
; __device__ __forceinline__ void item_attn(const Params& p, int l, int aidx) {
;     ...
;       auto sb_weights = [&](auto MASKED) {
; #pragma unroll
;         for (int n = 0; n < 2; ++n) {
;           const int qpos = qpos0 + 32 * wid + 16 * n + fr;
;           float wgt[4][4], excl[4][4], later[4], TT[4];
; #pragma unroll
;           for (int m = 0; m < 4; ++m) {
;             float f[4];
; #pragma unroll
;             for (int j = 0; j < 4; ++j) {
;               const float e = fexp(fminf(-z[m][n][j], 80.f));
;               const float sg = __builtin_amdgcn_rcpf(1.f + e);
;               if (decltype(MASKED)::value) {
;                 const bool ok = (kt * 64 + m * 16 + fq * 4 + j) < qpos;
;                 wgt[m][j] = ok ? sg : 0.f;
;                 f[j] = ok ? e * sg : 1.f;
;               } else { wgt[m][j] = sg; f[j] = e * sg; }
;             }
;             excl[m][3] = 1.f; excl[m][2] = f[3]; excl[m][1] = f[3] * f[2]; excl[m][0] = excl[m][1] * f[1];
;             const float G = excl[m][0] * f[0];
;             const float g1 = __shfl_xor(G, 16), g2 = __shfl_xor(G, 32), g3 = __shfl_xor(G, 48);
;             later[m] = ((fq ^ 1) > fq ? g1 : 1.f) * ((fq ^ 2) > fq ? g2 : 1.f) * ((fq ^ 3) > fq ? g3 : 1.f);
;             TT[m] = (G * g1) * (g2 * g3);
;           }
;           float lm[4]; lm[3] = carry[n]; lm[2] = lm[3] * TT[3]; lm[1] = lm[2] * TT[2]; lm[0] = lm[1] * TT[1];
; #pragma unroll
;           for (int m = 0; m < 4; ++m) {
;             const float base = later[m] * lm[m];
;             float pv[4];
; #pragma unroll
;             for (int j = 0; j < 4; ++j) pv[j] = wgt[m][j] * excl[m][j] * base;
;             pk[m][n][0] = pack2(pv[0], pv[1]); pk[m][n][1] = pack2(pv[2], pv[3]);
;           }
;           carry[n] = lm[0] * TT[0];
;         }
;       };
;       if (kt * 64 + 63 < qpos0 + 32 * wid) sb_weights(std::false_type{}); else sb_weights(std::true_type{});
	v_cndmask_b32_e64 v75, 1.0, v163, s[14:15]
	v_pk_mul_f32 v[166:167], v[166:167], v[174:175]
	v_mul_f32_e32 v174, v77, v79
	s_waitcnt lgkmcnt(4)
	v_cndmask_b32_e64 v77, 1.0, v74, s[16:17]
	v_mul_f32_e32 v75, v75, v77
	s_waitcnt lgkmcnt(3)
	v_cndmask_b32_e64 v77, 1.0, v78, s[18:19]
	v_mul_f32_e32 v99, v77, v75
	s_waitcnt lgkmcnt(2)
	v_cndmask_b32_e64 v75, 1.0, v183, s[16:17]
	s_waitcnt lgkmcnt(1)
	v_cndmask_b32_e64 v77, 1.0, v176, s[14:15]
	v_mul_f32_e32 v75, v77, v75
	s_waitcnt lgkmcnt(0)
	v_cndmask_b32_e64 v77, 1.0, v177, s[18:19]
	v_pk_mul_f32 v[176:177], v[182:183], v[176:177]
	v_mul_f32_e32 v165, v77, v75
	v_mov_b32_e32 v75, v176
	v_mov_b32_e32 v79, v177
	v_mul_f32_e32 v178, v224, v163
	v_pk_mul_f32 v[74:75], v[74:75], v[78:79]
	v_mov_b32_e32 v179, v90
	v_pk_mul_f32 v[78:79], v[178:179], v[74:75]
	v_mov_b32_e32 v163, v90
	v_mov_b32_e32 v77, v78
	v_mov_b32_e32 v175, v79
	v_pk_mul_f32 v[74:75], v[76:77], v[174:175]
	v_mul_f32_e32 v76, v97, v170
	v_pk_mul_f32 v[174:175], v[74:75], v[74:75] op_sel:[0,1] op_sel_hi:[1,0]
	v_mul_f32_e32 v74, v95, v172
	v_mov_b32_e32 v169, v174
	v_pk_mul_f32 v[72:73], v[72:73], v[168:169]
	v_mov_b32_e32 v95, v75
	v_mul_f32_e32 v74, v74, v73
	v_mul_f32_e32 v76, v76, v73
	v_mul_f32_e32 v77, v72, v73
	v_mul_f32_e32 v73, v101, v73
	v_cvt_pk_bf16_f32 v72, v74, v76
	v_cvt_pk_bf16_f32 v73, v77, v73
	v_mul_f32_e32 v76, v206, v222
	v_mul_f32_e32 v77, v219, v221
	v_pk_mul_f32 v[74:75], v[92:93], v[94:95]
	v_mov_b32_e32 v101, v79
	v_mul_f32_e32 v76, v76, v75
	v_mul_f32_e32 v77, v77, v75
	v_mul_f32_e32 v78, v74, v75
	v_mul_f32_e32 v75, v220, v75
	v_cvt_pk_bf16_f32 v74, v76, v77
	v_cvt_pk_bf16_f32 v75, v78, v75
	v_mul_f32_e32 v78, v184, v223
	v_mul_f32_e32 v92, v185, v199
	v_pk_mul_f32 v[76:77], v[98:99], v[100:101]
	v_mul_f32_e32 v93, v205, v218
	v_mul_f32_e32 v78, v78, v77
	v_mul_f32_e32 v79, v92, v77
	v_mul_f32_e32 v92, v76, v77
	v_mul_f32_e32 v77, v187, v77
	v_cvt_pk_bf16_f32 v76, v78, v79
	v_cvt_pk_bf16_f32 v77, v92, v77
	v_mul_f32_e32 v92, v203, v228
	v_pk_mul_f32 v[78:79], v[162:163], v[164:165]
	v_mov_b32_e32 v175, v96
	v_mul_f32_e32 v92, v92, v79
	v_mul_f32_e32 v93, v93, v79
	v_mul_f32_e32 v94, v78, v79
	v_mul_f32_e32 v79, v207, v79
	v_cvt_pk_bf16_f32 v78, v92, v93
	v_cvt_pk_bf16_f32 v79, v94, v79
	v_pk_mul_f32 v[92:93], v[166:167], v[174:175]
	s_mov_b64 s[0:1], 0
.LBB0_691:
	s_andn2_b64 vcc, exec, s[0:1]
	s_cbranch_vccnz .LBB0_693
	v_min_f32_e32 v64, 0x42e6d4ca, v160
	v_exp_f32_e32 v69, v64
	v_min_f32_e32 v64, 0x42e6d4ca, v161
	v_min_f32_e32 v66, 0x42e6d4ca, v158
	v_min_f32_e32 v65, 0x42e6d4ca, v159
	v_exp_f32_e32 v67, v64
	v_exp_f32_e32 v71, v66
	v_min_f32_e32 v66, 0x42e6d4ca, v157
	v_exp_f32_e32 v65, v65
	v_exp_f32_e32 v92, v66
	v_min_f32_e32 v66, 0x42e6d4ca, v156
	v_add_f32_e32 v64, 1.0, v69
	v_rcp_f32_e32 v77, v64
	v_add_f32_e32 v64, 1.0, v67
	v_exp_f32_e32 v66, v66
	v_rcp_f32_e32 v79, v64
	v_add_f32_e32 v64, 1.0, v65
	v_rcp_f32_e32 v73, v64
	v_add_f32_e32 v64, 1.0, v71
	v_min_f32_e32 v68, 0x42e6d4ca, v154
	v_rcp_f32_e32 v75, v64
	v_add_f32_e32 v64, 1.0, v92
	v_rcp_f32_e32 v94, v64
	v_add_f32_e32 v64, 1.0, v66
	v_exp_f32_e32 v97, v68
	v_min_f32_e32 v68, 0x42e6d4ca, v155
	v_rcp_f32_e32 v64, v64
	v_exp_f32_e32 v96, v68
	v_min_f32_e32 v68, 0x42e6d4ca, v151
	v_mul_f32_e32 v93, v66, v64
	v_add_f32_e32 v66, 1.0, v97
	v_rcp_f32_e32 v99, v66
	v_add_f32_e32 v66, 1.0, v96
	v_rcp_f32_e32 v98, v66
	v_min_f32_e32 v66, 0x42e6d4ca, v153
	v_exp_f32_e32 v66, v66
	v_min_f32_e32 v70, 0x42e6d4ca, v152
	v_exp_f32_e32 v100, v68
	v_add_f32_e32 v68, 1.0, v66
	v_rcp_f32_e32 v68, v68
	v_exp_f32_e32 v151, v70
	v_min_f32_e32 v72, 0x42e6d4ca, v148
	v_add_f32_e32 v70, 1.0, v100
	v_mul_f32_e32 v101, v66, v68
	v_add_f32_e32 v66, 1.0, v151
	v_rcp_f32_e32 v155, v66
	v_min_f32_e32 v66, 0x42e6d4ca, v150
	v_exp_f32_e32 v150, v66
	v_min_f32_e32 v66, 0x42e6d4ca, v149
	v_exp_f32_e32 v66, v66
	v_rcp_f32_e32 v152, v70
	v_min_f32_e32 v70, 0x42e6d4ca, v147
	v_exp_f32_e32 v147, v72
	v_min_f32_e32 v72, 0x42e6d4ca, v146
	v_exp_f32_e32 v146, v72
	v_exp_f32_e32 v156, v70
	v_add_f32_e32 v70, 1.0, v66
	v_rcp_f32_e32 v70, v70
	v_add_f32_e32 v72, 1.0, v147
	v_rcp_f32_e32 v149, v72
	v_add_f32_e32 v72, 1.0, v146
	v_rcp_f32_e32 v148, v72
	v_mul_f32_e32 v157, v66, v70
	v_add_f32_e32 v66, 1.0, v150
	v_add_f32_e32 v72, 1.0, v156
	v_rcp_f32_e32 v154, v66
	v_rcp_f32_e32 v158, v72
	v_pk_mul_f32 v[146:147], v[146:147], v[148:149]
	v_pk_mul_f32 v[96:97], v[96:97], v[98:99]
	v_pk_mul_f32 v[160:161], v[146:147], v[146:147] op_sel:[0,1] op_sel_hi:[1,0]
	v_pk_mul_f32 v[150:151], v[150:151], v[154:155]
	v_mov_b32_e32 v159, v160
	v_pk_mul_f32 v[156:157], v[156:157], v[158:159]
	v_pk_mul_f32 v[166:167], v[150:151], v[150:151] op_sel:[0,1] op_sel_hi:[1,0]
	v_pk_mul_f32 v[162:163], v[156:157], v[156:157] op_sel:[0,1] op_sel_hi:[1,0]
	v_mov_b32_e32 v153, v166
	ds_bpermute_b32 v163, v253, v162
	ds_bpermute_b32 v164, v252, v162
	ds_bpermute_b32 v165, v254, v162
	v_pk_mul_f32 v[100:101], v[100:101], v[152:153]
	v_mul_f32_e32 v68, v68, v166
	v_mul_f32_e32 v74, v100, v101
	ds_bpermute_b32 v76, v252, v74
	ds_bpermute_b32 v168, v253, v74
	ds_bpermute_b32 v170, v254, v74
	s_waitcnt lgkmcnt(5)
	v_cndmask_b32_e64 v66, 1.0, v163, s[16:17]
	s_waitcnt lgkmcnt(3)
	v_pk_mul_f32 v[162:163], v[162:163], v[164:165]
	v_cndmask_b32_e64 v72, 1.0, v164, s[14:15]
	v_mov_b32_e32 v169, v162
	v_mov_b32_e32 v171, v163
	v_mul_f32_e32 v66, v72, v66
	v_cndmask_b32_e64 v72, 1.0, v165, s[18:19]
	s_waitcnt lgkmcnt(2)
	v_mul_f32_e32 v164, v74, v76
	s_waitcnt lgkmcnt(0)
; __device__ __forceinline__ float fexp(float x) { return __builtin_amdgcn_exp2f(x * 1.44269504f); }
; __device__ __forceinline__ unsigned pack2(float a, float b) { unsigned r; asm volatile("v_cvt_pk_bf16_f32 %0, %1, %2" : "=v"(r) : "v"(a), "v"(b)); return r; }
; __device__ __forceinline__ void item_attn(const Params& p, int l, int aidx) {
;     ...
; #pragma unroll
;           for (int m = 0; m < 4; ++m) {
;             float f[4];
; #pragma unroll
;             for (int j = 0; j < 4; ++j) {
;               const float e = fexp(fminf(-z[m][n][j], 80.f));
;               const float sg = __builtin_amdgcn_rcpf(1.f + e);
;               if (decltype(MASKED)::value) {
;                 const bool ok = (kt * 64 + m * 16 + fq * 4 + j) < qpos;
;                 wgt[m][j] = ok ? sg : 0.f;
;                 f[j] = ok ? e * sg : 1.f;
;               } else { wgt[m][j] = sg; f[j] = e * sg; }
;             }
;             excl[m][3] = 1.f; excl[m][2] = f[3]; excl[m][1] = f[3] * f[2]; excl[m][0] = excl[m][1] * f[1];
;             const float G = excl[m][0] * f[0];
;             const float g1 = __shfl_xor(G, 16), g2 = __shfl_xor(G, 32), g3 = __shfl_xor(G, 48);
;             later[m] = ((fq ^ 1) > fq ? g1 : 1.f) * ((fq ^ 2) > fq ? g2 : 1.f) * ((fq ^ 3) > fq ? g3 : 1.f);
;             TT[m] = (G * g1) * (g2 * g3);
;           }
;           float lm[4]; lm[3] = carry[n]; lm[2] = lm[3] * TT[3]; lm[1] = lm[2] * TT[2]; lm[0] = lm[1] * TT[1];
; #pragma unroll
;           for (int m = 0; m < 4; ++m) {
;             const float base = later[m] * lm[m];
;             float pv[4];
; #pragma unroll
;             for (int j = 0; j < 4; ++j) pv[j] = wgt[m][j] * excl[m][j] * base;
;             pk[m][n][0] = pack2(pv[0], pv[1]); pk[m][n][1] = pack2(pv[2], pv[3]);
;           }
;           carry[n] = lm[0] * TT[0];
	v_pk_mul_f32 v[162:163], v[168:169], v[170:171]
	v_mov_b32_e32 v165, v91
	v_pk_mul_f32 v[162:163], v[164:165], v[162:163]
	v_pk_mul_f32 v[164:165], v[96:97], v[96:97] op_sel:[0,1] op_sel_hi:[1,0]
	v_mul_f32_e32 v147, v72, v66
	v_cndmask_b32_e64 v66, 1.0, v76, s[14:15]
	v_cndmask_b32_e64 v72, 1.0, v168, s[16:17]
	v_mov_b32_e32 v95, v164
	v_mul_f32_e32 v66, v66, v72
	v_cndmask_b32_e64 v72, 1.0, v170, s[18:19]
	v_pk_mul_f32 v[92:93], v[92:93], v[94:95]
	v_mul_f32_e32 v151, v72, v66
	v_mul_f32_e32 v66, v92, v93
	ds_bpermute_b32 v72, v252, v66
	ds_bpermute_b32 v74, v253, v66
	ds_bpermute_b32 v78, v254, v66
	v_mul_f32_e32 v76, v152, v101
	v_mov_b32_e32 v101, v162
	s_waitcnt lgkmcnt(2)
	v_cndmask_b32_e64 v92, 1.0, v72, s[14:15]
	s_waitcnt lgkmcnt(1)
	v_cndmask_b32_e64 v95, 1.0, v74, s[16:17]
	v_mul_f32_e32 v100, v66, v72
	s_waitcnt lgkmcnt(0)
	v_mul_f32_e32 v152, v74, v78
	v_mov_b32_e32 v153, v163
	v_mul_f32_e32 v92, v92, v95
	v_cndmask_b32_e64 v95, 1.0, v78, s[18:19]
	v_pk_mul_f32 v[100:101], v[100:101], v[152:153]
	v_mul_f32_e32 v97, v95, v92
	v_mul_f32_e32 v66, v94, v93
	v_mov_b32_e32 v92, v99
	v_mov_b32_e32 v93, v101
	v_mul_f32_e32 v64, v64, v164
	v_pk_mul_f32 v[92:93], v[92:93], v[96:97]
	v_mov_b32_e32 v162, v155
	v_mul_f32_e32 v97, v66, v93
	v_mul_f32_e32 v156, v64, v93
	v_mul_f32_e32 v161, v92, v93
	v_mul_f32_e32 v164, v98, v93
	v_pk_mul_f32 v[92:93], v[162:163], v[150:151]
	v_mul_f32_e32 v64, v158, v157
	v_mul_f32_e32 v162, v76, v93
	v_mul_f32_e32 v163, v68, v93
	v_mul_f32_e32 v165, v92, v93
	v_mul_f32_e32 v166, v154, v93
	v_mov_b32_e32 v92, v149
	v_mov_b32_e32 v93, v91
	v_pk_mul_f32 v[92:93], v[92:93], v[146:147]
	v_min_f32_e32 v137, 0x42e6d4ca, v137
	v_mul_f32_e32 v167, v64, v93
	v_mul_f32_e32 v64, v70, v160
	v_mul_f32_e32 v160, v64, v93
	v_min_f32_e32 v64, 0x42e6d4ca, v145
	v_exp_f32_e32 v68, v64
	v_min_f32_e32 v64, 0x42e6d4ca, v144
	v_mul_f32_e32 v168, v92, v93
	v_min_f32_e32 v92, 0x42e6d4ca, v141
	v_exp_f32_e32 v66, v64
	v_add_f32_e32 v64, 1.0, v68
	v_rcp_f32_e32 v76, v64
	v_min_f32_e32 v64, 0x42e6d4ca, v142
	v_exp_f32_e32 v94, v92
	v_min_f32_e32 v92, 0x42e6d4ca, v140
	v_exp_f32_e32 v70, v64
	v_min_f32_e32 v64, 0x42e6d4ca, v143
	v_exp_f32_e32 v92, v92
	v_exp_f32_e32 v64, v64
	v_mul_f32_e32 v169, v148, v93
	v_add_f32_e32 v93, 1.0, v94
	v_add_f32_e32 v72, 1.0, v66
	v_rcp_f32_e32 v96, v93
	v_add_f32_e32 v93, 1.0, v92
	v_rcp_f32_e32 v78, v72
	v_add_f32_e32 v72, 1.0, v70
	v_rcp_f32_e32 v170, v93
	v_min_f32_e32 v93, 0x42e6d4ca, v139
	v_min_f32_e32 v136, 0x42e6d4ca, v136
	v_rcp_f32_e32 v74, v72
	v_add_f32_e32 v72, 1.0, v64
	v_rcp_f32_e32 v72, v72
	v_exp_f32_e32 v99, v93
	v_min_f32_e32 v93, 0x42e6d4ca, v138
	v_exp_f32_e32 v138, v137
	v_exp_f32_e32 v137, v136
	v_min_f32_e32 v135, 0x42e6d4ca, v135
	v_min_f32_e32 v134, 0x42e6d4ca, v134
	v_add_f32_e32 v139, 1.0, v137
	v_pk_mul_f32 v[70:71], v[70:71], v[74:75]
	v_pk_mul_f32 v[146:147], v[64:65], v[72:73]
	v_rcp_f32_e32 v171, v139
	v_exp_f32_e32 v135, v135
	v_min_f32_e32 v133, 0x42e6d4ca, v133
	v_pk_mul_f32 v[66:67], v[66:67], v[78:79]
	v_pk_mul_f32 v[148:149], v[70:71], v[146:147]
	v_exp_f32_e32 v134, v134
	v_min_f32_e32 v132, 0x42e6d4ca, v132
	v_min_f32_e32 v130, 0x42e6d4ca, v130
	v_pk_mul_f32 v[68:69], v[68:69], v[76:77]
	v_pk_mul_f32 v[150:151], v[66:67], v[148:149]
	v_exp_f32_e32 v133, v133
	v_min_f32_e32 v131, 0x42e6d4ca, v131
	v_pk_mul_f32 v[152:153], v[68:69], v[150:151]
	v_exp_f32_e32 v132, v132
	v_exp_f32_e32 v130, v130
	ds_bpermute_b32 v155, v252, v153
	ds_bpermute_b32 v157, v253, v153
	v_mul_f32_e32 v139, v137, v171
	v_add_f32_e32 v137, 1.0, v135
	v_exp_f32_e32 v131, v131
	ds_bpermute_b32 v159, v254, v153
	v_rcp_f32_e32 v141, v137
	v_add_f32_e32 v137, 1.0, v134
	v_rcp_f32_e32 v140, v137
	v_add_f32_e32 v137, 1.0, v133
	v_rcp_f32_e32 v172, v137
	v_add_f32_e32 v137, 1.0, v132
	v_add_f32_e32 v64, 1.0, v130
	v_rcp_f32_e32 v142, v137
	v_add_f32_e32 v137, 1.0, v131
	v_rcp_f32_e32 v144, v64
	s_waitcnt lgkmcnt(2)
	v_cndmask_b32_e64 v64, 1.0, v155, s[14:15]
	s_waitcnt lgkmcnt(1)
	v_cndmask_b32_e64 v65, 1.0, v157, s[16:17]
	v_rcp_f32_e32 v145, v137
	v_mul_f32_e32 v64, v64, v65
	s_waitcnt lgkmcnt(0)
	v_cndmask_b32_e64 v65, 1.0, v159, s[18:19]
	v_pk_mul_f32 v[100:101], v[100:101], v[100:101] op_sel:[0,1] op_sel_hi:[1,0]
	ds_bpermute_b32 v154, v252, v152
	v_mul_f32_e32 v65, v65, v64
	v_mov_b32_e32 v64, v73
	v_pk_mov_b32 v[66:67], v[70:71], v[100:101] op_sel:[1,0]
	v_mul_f32_e32 v68, v77, v151
	v_mul_f32_e32 v69, v79, v149
	v_pk_mul_f32 v[64:65], v[64:65], v[66:67]
	ds_bpermute_b32 v158, v254, v152
	v_mul_f32_e32 v66, v68, v65
	v_mul_f32_e32 v67, v69, v65
	v_mul_f32_e32 v64, v64, v65
	v_mul_f32_e32 v65, v75, v65
	v_cvt_pk_bf16_f32 v68, v66, v67
	v_cvt_pk_bf16_f32 v69, v64, v65
	v_cvt_pk_bf16_f32 v70, v97, v156
	ds_bpermute_b32 v156, v253, v152
	v_pk_mul_f32 v[130:131], v[130:131], v[144:145]
	s_waitcnt lgkmcnt(2)
; __device__ __forceinline__ float fexp(float x) { return __builtin_amdgcn_exp2f(x * 1.44269504f); }
; __device__ __forceinline__ unsigned pack2(float a, float b) { unsigned r; asm volatile("v_cvt_pk_bf16_f32 %0, %1, %2" : "=v"(r) : "v"(a), "v"(b)); return r; }
; __device__ __forceinline__ void item_attn(const Params& p, int l, int aidx) {
;     ...
; #pragma unroll
;           for (int m = 0; m < 4; ++m) {
;             float f[4];
; #pragma unroll
;             for (int j = 0; j < 4; ++j) {
;               const float e = fexp(fminf(-z[m][n][j], 80.f));
;               const float sg = __builtin_amdgcn_rcpf(1.f + e);
;               if (decltype(MASKED)::value) {
;                 const bool ok = (kt * 64 + m * 16 + fq * 4 + j) < qpos;
;                 wgt[m][j] = ok ? sg : 0.f;
;                 f[j] = ok ? e * sg : 1.f;
;               } else { wgt[m][j] = sg; f[j] = e * sg; }
;             }
;             excl[m][3] = 1.f; excl[m][2] = f[3]; excl[m][1] = f[3] * f[2]; excl[m][0] = excl[m][1] * f[1];
;             const float G = excl[m][0] * f[0];
;             const float g1 = __shfl_xor(G, 16), g2 = __shfl_xor(G, 32), g3 = __shfl_xor(G, 48);
;             later[m] = ((fq ^ 1) > fq ? g1 : 1.f) * ((fq ^ 2) > fq ? g2 : 1.f) * ((fq ^ 3) > fq ? g3 : 1.f);
;             TT[m] = (G * g1) * (g2 * g3);
;           }
;           float lm[4]; lm[3] = carry[n]; lm[2] = lm[3] * TT[3]; lm[1] = lm[2] * TT[2]; lm[0] = lm[1] * TT[1];
; #pragma unroll
;           for (int m = 0; m < 4; ++m) {
;             const float base = later[m] * lm[m];
;             float pv[4];
; #pragma unroll
;             for (int j = 0; j < 4; ++j) pv[j] = wgt[m][j] * excl[m][j] * base;
;             pk[m][n][0] = pack2(pv[0], pv[1]); pk[m][n][1] = pack2(pv[2], pv[3]);
;           }
;           carry[n] = lm[0] * TT[0];
	v_pk_mul_f32 v[152:153], v[152:153], v[154:155]
	v_cndmask_b32_e64 v73, 1.0, v154, s[14:15]
	v_pk_mul_f32 v[154:155], v[130:131], v[130:131] op_sel:[0,1] op_sel_hi:[1,0]
	v_mul_f32_e32 v133, v133, v172
	v_mov_b32_e32 v143, v154
	v_pk_mul_f32 v[132:133], v[132:133], v[142:143]
	v_cvt_pk_bf16_f32 v71, v161, v164
	v_cvt_pk_bf16_f32 v64, v162, v163
	v_cvt_pk_bf16_f32 v65, v165, v166
	v_cvt_pk_bf16_f32 v66, v167, v160
	s_waitcnt lgkmcnt(0)
	v_pk_mul_f32 v[160:161], v[156:157], v[158:159]
	v_cndmask_b32_e64 v75, 1.0, v156, s[16:17]
	v_pk_mul_f32 v[156:157], v[132:133], v[132:133] op_sel:[0,1] op_sel_hi:[1,0]
	v_mul_f32_e32 v73, v73, v75
	v_cndmask_b32_e64 v75, 1.0, v158, s[18:19]
	ds_bpermute_b32 v157, v253, v156
	ds_bpermute_b32 v158, v252, v156
	v_add_f32_e32 v136, 1.0, v138
	v_rcp_f32_e32 v136, v136
	v_mul_f32_e32 v75, v75, v73
	v_mul_f32_e32 v73, v76, v150
	s_waitcnt lgkmcnt(1)
	v_cndmask_b32_e64 v76, 1.0, v157, s[16:17]
	s_waitcnt lgkmcnt(0)
	v_cndmask_b32_e64 v77, 1.0, v158, s[14:15]
	v_mul_f32_e32 v97, v77, v76
	v_pk_mul_f32 v[76:77], v[134:135], v[140:141]
	v_exp_f32_e32 v98, v93
	v_mul_f32_e32 v101, v78, v148
	v_pk_mul_f32 v[78:79], v[76:77], v[76:77] op_sel:[0,1] op_sel_hi:[1,0]
	v_mul_f32_e32 v95, v92, v170
	v_mov_b32_e32 v137, v78
	v_pk_mul_f32 v[134:135], v[138:139], v[136:137]
	v_add_f32_e32 v92, 1.0, v99
	ds_bpermute_b32 v159, v254, v156
	v_mul_f32_e32 v79, v134, v135
	v_rcp_f32_e32 v93, v92
	v_add_f32_e32 v92, 1.0, v98
	ds_bpermute_b32 v132, v252, v79
	ds_bpermute_b32 v138, v253, v79
	v_rcp_f32_e32 v92, v92
	ds_bpermute_b32 v148, v254, v79
	s_waitcnt lgkmcnt(3)
	v_cndmask_b32_e64 v131, 1.0, v159, s[18:19]
	v_pk_mul_f32 v[150:151], v[156:157], v[158:159]
	v_mul_f32_e32 v131, v131, v97
	s_waitcnt lgkmcnt(2)
	v_cndmask_b32_e64 v77, 1.0, v132, s[14:15]
	s_waitcnt lgkmcnt(1)
	v_cndmask_b32_e64 v97, 1.0, v138, s[16:17]
	v_mov_b32_e32 v139, v150
	v_mov_b32_e32 v149, v151
	v_pk_mul_f32 v[98:99], v[98:99], v[92:93]
	v_mul_f32_e32 v77, v77, v97
	s_waitcnt lgkmcnt(0)
	v_cndmask_b32_e64 v97, 1.0, v148, s[18:19]
	v_pk_mul_f32 v[138:139], v[138:139], v[148:149]
	v_pk_mul_f32 v[148:149], v[98:99], v[98:99] op_sel:[0,1] op_sel_hi:[1,0]
	v_mul_f32_e32 v77, v97, v77
	v_mov_b32_e32 v97, v148
	v_pk_mul_f32 v[94:95], v[94:95], v[96:97]
	v_mul_f32_e32 v156, v79, v132
	v_mul_f32_e32 v79, v94, v95
	ds_bpermute_b32 v94, v252, v79
	ds_bpermute_b32 v97, v253, v79
	ds_bpermute_b32 v128, v254, v79
	v_mov_b32_e32 v157, v90
	v_mul_f32_e32 v132, v171, v78
	s_waitcnt lgkmcnt(2)
	v_cndmask_b32_e64 v78, 1.0, v94, s[14:15]
	s_waitcnt lgkmcnt(1)
	v_cndmask_b32_e64 v99, 1.0, v97, s[16:17]
	v_pk_mul_f32 v[138:139], v[156:157], v[138:139]
	v_mul_f32_e32 v78, v78, v99
	s_waitcnt lgkmcnt(0)
	v_cndmask_b32_e64 v99, 1.0, v128, s[18:19]
	v_mul_f32_e32 v99, v99, v78
	v_mul_f32_e32 v78, v79, v94
	v_mul_f32_e32 v128, v97, v128
	v_mov_b32_e32 v79, v138
	v_mov_b32_e32 v129, v139
	v_pk_mul_f32 v[78:79], v[78:79], v[128:129]
	v_mul_f32_e32 v96, v96, v95
	v_pk_mul_f32 v[94:95], v[78:79], v[78:79] op_sel:[0,1] op_sel_hi:[1,0]
	v_cvt_pk_bf16_f32 v67, v168, v169
	v_mul_f32_e32 v97, v170, v148
	v_mov_b32_e32 v147, v94
	v_pk_mul_f32 v[74:75], v[74:75], v[146:147]
	v_mov_b32_e32 v138, v141
	v_mul_f32_e32 v78, v101, v75
	v_mul_f32_e32 v73, v73, v75
	v_mul_f32_e32 v74, v74, v75
	v_mul_f32_e32 v75, v72, v75
	v_cvt_pk_bf16_f32 v72, v73, v78
	v_mov_b32_e32 v78, v93
	v_cvt_pk_bf16_f32 v73, v74, v75
	v_pk_mul_f32 v[74:75], v[78:79], v[98:99]
	v_mul_f32_e32 v127, v136, v135
	v_mul_f32_e32 v78, v96, v75
	v_mul_f32_e32 v79, v97, v75
	v_pk_mul_f32 v[76:77], v[138:139], v[76:77]
	v_mul_f32_e32 v93, v74, v75
	v_mul_f32_e32 v75, v92, v75
	v_cvt_pk_bf16_f32 v74, v78, v79
	v_mul_f32_e32 v78, v127, v77
	v_mul_f32_e32 v79, v132, v77
	v_cvt_pk_bf16_f32 v75, v93, v75
	v_mul_f32_e32 v92, v76, v77
	v_mul_f32_e32 v77, v140, v77
	v_cvt_pk_bf16_f32 v76, v78, v79
	v_pk_mov_b32 v[78:79], v[144:145], v[90:91] op_sel:[1,0]
	v_cvt_pk_bf16_f32 v77, v92, v77
	v_mul_f32_e32 v92, v142, v133
	v_pk_mul_f32 v[78:79], v[78:79], v[130:131]
	v_mul_f32_e32 v91, v172, v154
	v_pk_mul_f32 v[152:153], v[152:153], v[160:161]
	v_mul_f32_e32 v90, v92, v79
	v_mul_f32_e32 v91, v91, v79
	v_mul_f32_e32 v92, v78, v79
	v_mul_f32_e32 v79, v144, v79
	v_mov_b32_e32 v95, v100
	v_cvt_pk_bf16_f32 v78, v90, v91
	v_cvt_pk_bf16_f32 v79, v92, v79
	v_pk_mul_f32 v[92:93], v[152:153], v[94:95]

; __device__ __forceinline__ float fexp(float x) { return __builtin_amdgcn_exp2f(x * 1.44269504f); }
; __device__ __forceinline__ void item_attn(const Params& p, int l, int aidx) {
;     ...
;     if (!wave_done && kt * 64 < wave_qmax) {
;       f32x4 z[4][2];
; #pragma unroll
;       for (int m = 0; m < 4; ++m) {
;         bf16x8 a0 = *reinterpret_cast<const bf16x8*>(Ks + (m * 16 + fr) * 72 + fq * 8);
;         bf16x8 a1 = *reinterpret_cast<const bf16x8*>(Ks + (m * 16 + fr) * 72 + 32 + fq * 8);
; #pragma unroll
;         for (int n = 0; n < 2; ++n) {
;           f32x4 zz = f32x4{0.f, 0.f, 0.f, 0.f};
;           zz = __builtin_amdgcn_mfma_f32_16x16x32_bf16(a0, qf[n][0], zz, 0, 0, 0);
;           zz = __builtin_amdgcn_mfma_f32_16x16x32_bf16(a1, qf[n][1], zz, 0, 0, 0);
;           z[m][n] = zz;
;         }
;       }
;       unsigned pk[4][2][2];
;       auto sb_weights = [&](auto MASKED) {
; #pragma unroll
;         for (int n = 0; n < 2; ++n) {
;           const int qpos = qpos0 + 32 * wid + 16 * n + fr;
;           float wgt[4][4], excl[4][4], later[4], TT[4];
; #pragma unroll
;           for (int m = 0; m < 4; ++m) {
;             float f[4];
; #pragma unroll
;             for (int j = 0; j < 4; ++j) {
;               const float e = fexp(fminf(-z[m][n][j], 80.f));
;               const float sg = __builtin_amdgcn_rcpf(1.f + e);
;               if (decltype(MASKED)::value) {
;                 const bool ok = (kt * 64 + m * 16 + fq * 4 + j) < qpos;
;                 wgt[m][j] = ok ? sg : 0.f;
;                 f[j] = ok ? e * sg : 1.f;
;               } else { wgt[m][j] = sg; f[j] = e * sg; }
;             }
;             excl[m][3] = 1.f; excl[m][2] = f[3]; excl[m][1] = f[3] * f[2]; excl[m][0] = excl[m][1] * f[1];
;             const float G = excl[m][0] * f[0];
;             const float g1 = __shfl_xor(G, 16), g2 = __shfl_xor(G, 32), g3 = __shfl_xor(G, 48);
;             later[m] = ((fq ^ 1) > fq ? g1 : 1.f) * ((fq ^ 2) > fq ? g2 : 1.f) * ((fq ^ 3) > fq ? g3 : 1.f);
;             TT[m] = (G * g1) * (g2 * g3);
.LBB0_760:
	s_andn2_b64 vcc, exec, s[4:5]
	s_mov_b64 s[0:1], -1
	s_cbranch_vccnz .LBB0_767
	s_cmp_ge_i32 s49, s51
	s_mov_b64 s[0:1], 0
	s_cbranch_scc1 .LBB0_767
	ds_read_b128 v[64:67], v118
	ds_read_b128 v[68:71], v118 offset:64
	s_mov_b32 s100, 0xbfb8aa3b
	s_nop 0
	s_nop 0
	s_waitcnt lgkmcnt(1)
	v_mfma_f32_16x16x32_bf16 v[72:75], v[64:67], v[4:7], 0
	s_nop 0
	s_add_i32 s0, s49, 63
	s_cmp_lt_i32 s0, s50
	v_mfma_f32_16x16x32_bf16 v[64:67], v[64:67], v[12:15], 0
	s_nop 0
	s_nop 0
	s_nop 0
	s_waitcnt lgkmcnt(0)
	v_mfma_f32_16x16x32_bf16 v[72:75], v[68:71], v[0:3], v[72:75]
	s_nop 0
	s_mov_b64 s[0:1], -1
	v_mfma_f32_16x16x32_bf16 v[64:67], v[68:71], v[8:11], v[64:67]
	ds_read_b128 v[68:71], v118 offset:2304
	ds_read_b128 v[76:79], v118 offset:2368
	s_nop 0
	s_nop 1
	s_nop 0
	s_waitcnt lgkmcnt(1)
	v_mfma_f32_16x16x32_bf16 v[92:95], v[68:71], v[4:7], 0
	v_pk_mul_f32 v[160:161], v[72:73], s[100:101] op_sel_hi:[1,0]
	s_nop 0
	v_pk_mul_f32 v[158:159], v[74:75], s[100:101] op_sel:[1,0] op_sel_hi:[0,0]
	v_mfma_f32_16x16x32_bf16 v[68:71], v[68:71], v[12:15], 0
	s_nop 0
	v_pk_mul_f32 v[144:145], v[64:65], s[100:101] op_sel:[1,0] op_sel_hi:[0,0]
	s_nop 0
	s_waitcnt lgkmcnt(0)
	v_mfma_f32_16x16x32_bf16 v[92:95], v[76:79], v[0:3], v[92:95]
	v_pk_mul_f32 v[142:143], v[66:67], s[100:101] op_sel_hi:[1,0]
	v_mfma_f32_16x16x32_bf16 v[68:71], v[76:79], v[8:11], v[68:71]
	ds_read_b128 v[76:79], v118 offset:4608
	ds_read_b128 v[96:99], v118 offset:4672
	s_nop 3
	s_nop 0
	v_pk_mul_f32 v[156:157], v[92:93], s[100:101] op_sel:[1,0] op_sel_hi:[0,0]
	s_waitcnt lgkmcnt(1)
	v_mfma_f32_16x16x32_bf16 v[128:131], v[76:79], v[4:7], 0
	s_nop 0
	v_pk_mul_f32 v[154:155], v[94:95], s[100:101] op_sel_hi:[1,0]
	v_mfma_f32_16x16x32_bf16 v[76:79], v[76:79], v[12:15], 0
	s_waitcnt lgkmcnt(0)
	v_mfma_f32_16x16x32_bf16 v[130:133], v[96:99], v[0:3], v[128:131]
	v_mfma_f32_16x16x32_bf16 v[76:79], v[96:99], v[8:11], v[76:79]
	ds_read_b128 v[96:99], v118 offset:6912
	ds_read_b128 v[134:137], v118 offset:6976
	s_nop 0
	s_nop 0
	s_waitcnt lgkmcnt(1)
	v_mfma_f32_16x16x32_bf16 v[138:141], v[96:99], v[4:7], 0
	s_nop 0
	v_mul_f32_e32 v151, s100, v130
	v_mul_f32_e32 v153, s100, v131
	v_mfma_f32_16x16x32_bf16 v[96:99], v[96:99], v[12:15], 0
	s_nop 0
	s_nop 0
	v_mul_f32_e32 v152, s100, v132
	s_waitcnt lgkmcnt(0)
	v_mfma_f32_16x16x32_bf16 v[138:141], v[134:137], v[0:3], v[138:141]
	v_mul_f32_e32 v150, s100, v133
	v_mfma_f32_16x16x32_bf16 v[96:99], v[134:137], v[8:11], v[96:99]
	s_nop 0
	s_nop 4
	v_mul_f32_e32 v147, s100, v138
	v_mul_f32_e32 v149, s100, v139
	v_mul_f32_e32 v148, s100, v140
	v_mul_f32_e32 v146, s100, v141
	s_nop 0
	v_pk_mul_f32 v[140:141], v[68:69], s[100:101] op_sel:[1,0] op_sel_hi:[0,0]
	s_nop 0
	v_pk_mul_f32 v[138:139], v[70:71], s[100:101] op_sel:[1,0] op_sel_hi:[0,0]
	v_pk_mul_f32 v[136:137], v[76:77], s[100:101] op_sel:[1,0] op_sel_hi:[0,0]
	s_nop 0
	v_pk_mul_f32 v[134:135], v[78:79], s[100:101] op_sel:[1,0] op_sel_hi:[0,0]
	s_nop 0
	v_pk_mul_f32 v[132:133], v[96:97], s[100:101] op_sel_hi:[1,0]
	s_nop 0
	v_pk_mul_f32 v[130:131], v[98:99], s[100:101] op_sel:[1,0] op_sel_hi:[0,0]
	s_cbranch_scc1 .LBB0_764
	v_min_f32_e32 v64, 0x42e6d4ca, v160
	v_exp_f32_e32 v69, v64
	v_min_f32_e32 v64, 0x42e6d4ca, v161
	v_exp_f32_e32 v67, v64
	v_min_f32_e32 v64, 0x42e6d4ca, v159
	v_add_f32_e32 v65, 1.0, v69
	v_rcp_f32_e32 v73, v65
	v_exp_f32_e32 v65, v64
	v_min_f32_e32 v66, 0x42e6d4ca, v157
	v_add_f32_e32 v64, 1.0, v67
	v_exp_f32_e32 v66, v66
	v_rcp_f32_e32 v75, v64
	v_add_f32_e32 v64, 1.0, v65
	v_rcp_f32_e32 v77, v64
	v_min_f32_e32 v64, 0x42e6d4ca, v158
	v_min_f32_e32 v68, 0x42e6d4ca, v156
	v_exp_f32_e32 v71, v64
	v_add_f32_e32 v64, 1.0, v66
	v_rcp_f32_e32 v64, v64
	v_exp_f32_e32 v68, v68
	v_add_u32_e32 v178, s49, v114
	v_add_u32_e32 v180, 16, v178
	v_cmp_lt_i32_e32 vcc, v180, v85
	v_min_f32_e32 v72, 0x42e6d4ca, v154
	s_nop 0
	v_cndmask_b32_e32 v70, 0, v64, vcc
	v_mul_f32_e32 v64, v66, v64
	v_add_f32_e32 v66, 1.0, v68
	v_rcp_f32_e32 v66, v66
	v_exp_f32_e32 v72, v72
	v_add_u32_e32 v181, 17, v178
	v_cndmask_b32_e32 v64, 1.0, v64, vcc
	v_cmp_lt_i32_e32 vcc, v181, v85
	v_min_f32_e32 v76, 0x42e6d4ca, v155
	s_nop 0
	v_cndmask_b32_e32 v74, 0, v66, vcc
	v_mul_f32_e32 v66, v68, v66
	v_add_f32_e32 v68, 1.0, v72
	v_rcp_f32_e32 v68, v68
	v_exp_f32_e32 v76, v76
	v_add_u32_e32 v182, 18, v178
	v_cndmask_b32_e32 v66, 1.0, v66, vcc
	v_cmp_lt_i32_e32 vcc, v182, v85
	v_add_u32_e32 v183, 19, v178
	v_min_f32_e32 v98, 0x42e6d4ca, v153
	v_cndmask_b32_e32 v92, 0, v68, vcc
	v_mul_f32_e32 v68, v72, v68
	v_add_f32_e32 v72, 1.0, v76
	v_rcp_f32_e32 v72, v72
	v_cndmask_b32_e32 v68, 1.0, v68, vcc
	v_cmp_lt_i32_e32 vcc, v183, v85
	v_exp_f32_e32 v98, v98
	s_nop 0
	v_cndmask_b32_e32 v78, 0, v72, vcc
	v_mul_f32_e32 v72, v76, v72
	v_cndmask_b32_e32 v94, 1.0, v72, vcc
	v_mul_f32_e32 v68, v94, v68
	v_mul_f32_e32 v66, v66, v68
	v_mul_f32_e32 v64, v64, v66
	ds_bpermute_b32 v72, v252, v64
	ds_bpermute_b32 v76, v253, v64
	ds_bpermute_b32 v95, v254, v64
	v_add_u32_e32 v184, 32, v178
	v_cmp_lt_i32_e32 vcc, v184, v85
	s_waitcnt lgkmcnt(2)
	v_cndmask_b32_e64 v93, 1.0, v72, s[14:15]
	s_waitcnt lgkmcnt(1)
	v_cndmask_b32_e64 v96, 1.0, v76, s[16:17]
	v_mul_f32_e32 v93, v93, v96
	v_min_f32_e32 v96, 0x42e6d4ca, v151
	v_exp_f32_e32 v96, v96
	s_waitcnt lgkmcnt(0)
; __device__ __forceinline__ float fexp(float x) { return __builtin_amdgcn_exp2f(x * 1.44269504f); }
; __device__ __forceinline__ void item_attn(const Params& p, int l, int aidx) {
;     ...
; #pragma unroll
;           for (int m = 0; m < 4; ++m) {
;             float f[4];
; #pragma unroll
;             for (int j = 0; j < 4; ++j) {
;               const float e = fexp(fminf(-z[m][n][j], 80.f));
;               const float sg = __builtin_amdgcn_rcpf(1.f + e);
;               if (decltype(MASKED)::value) {
;                 const bool ok = (kt * 64 + m * 16 + fq * 4 + j) < qpos;
;                 wgt[m][j] = ok ? sg : 0.f;
;                 f[j] = ok ? e * sg : 1.f;
;               } else { wgt[m][j] = sg; f[j] = e * sg; }
;             }
;             excl[m][3] = 1.f; excl[m][2] = f[3]; excl[m][1] = f[3] * f[2]; excl[m][0] = excl[m][1] * f[1];
;             const float G = excl[m][0] * f[0];
;             const float g1 = __shfl_xor(G, 16), g2 = __shfl_xor(G, 32), g3 = __shfl_xor(G, 48);
;             later[m] = ((fq ^ 1) > fq ? g1 : 1.f) * ((fq ^ 2) > fq ? g2 : 1.f) * ((fq ^ 3) > fq ? g3 : 1.f);
;             TT[m] = (G * g1) * (g2 * g3);
;           }
	v_cndmask_b32_e64 v97, 1.0, v95, s[18:19]
	v_mul_f32_e32 v93, v97, v93
	v_min_f32_e32 v99, 0x42e6d4ca, v152
	v_add_f32_e32 v97, 1.0, v96
	v_rcp_f32_e32 v97, v97
	v_exp_f32_e32 v99, v99
	v_add_u32_e32 v185, 33, v178
	v_cndmask_b32_e32 v101, 0, v97, vcc
	v_mul_f32_e32 v96, v96, v97
	v_add_f32_e32 v97, 1.0, v98
	v_rcp_f32_e32 v97, v97
	v_cndmask_b32_e32 v96, 1.0, v96, vcc
	v_cmp_lt_i32_e32 vcc, v185, v85
	v_add_u32_e32 v186, 34, v178
	v_mul_f32_e32 v164, v76, v95
	v_cndmask_b32_e32 v169, 0, v97, vcc
	v_mul_f32_e32 v97, v98, v97
	v_add_f32_e32 v98, 1.0, v99
	v_rcp_f32_e32 v100, v98
	v_min_f32_e32 v98, 0x42e6d4ca, v150
	v_exp_f32_e32 v162, v98
	v_cndmask_b32_e32 v97, 1.0, v97, vcc
	v_cmp_lt_i32_e32 vcc, v186, v85
	v_mul_f32_e32 v99, v99, v100
	v_min_f32_e32 v76, 0x42e6d4ca, v147
	v_cndmask_b32_e32 v98, 0, v100, vcc
	v_add_f32_e32 v100, 1.0, v162
	v_rcp_f32_e32 v100, v100
	v_add_u32_e32 v187, 35, v178
	v_cndmask_b32_e32 v99, 1.0, v99, vcc
	v_cmp_lt_i32_e32 vcc, v187, v85
	v_exp_f32_e32 v76, v76
	v_add_u32_e32 v202, 48, v178
	v_cndmask_b32_e32 v199, 0, v100, vcc
	v_mul_f32_e32 v100, v162, v100
	v_cndmask_b32_e32 v100, 1.0, v100, vcc
	v_mul_f32_e32 v200, v100, v99
	v_min_f32_e32 v99, 0x42e6d4ca, v149
	v_add_f32_e32 v95, 1.0, v76
	v_rcp_f32_e32 v95, v95
	v_exp_f32_e32 v99, v99
	v_cmp_lt_i32_e32 vcc, v202, v85
	v_min_f32_e32 v165, 0x42e6d4ca, v148
	v_mul_f32_e32 v76, v76, v95
	v_cndmask_b32_e32 v203, 0, v95, vcc
	v_add_f32_e32 v95, 1.0, v99
	v_rcp_f32_e32 v95, v95
	v_exp_f32_e32 v165, v165
	v_add_u32_e32 v204, 49, v178
	v_cndmask_b32_e32 v76, 1.0, v76, vcc
	v_cmp_lt_i32_e32 vcc, v204, v85
	v_min_f32_e32 v167, 0x42e6d4ca, v146
	s_nop 0
	v_cndmask_b32_e32 v205, 0, v95, vcc
	v_mul_f32_e32 v95, v99, v95
	v_add_f32_e32 v99, 1.0, v165
	v_rcp_f32_e32 v99, v99
	v_exp_f32_e32 v167, v167
	v_add_u32_e32 v206, 50, v178
	v_cndmask_b32_e32 v95, 1.0, v95, vcc
	v_cmp_lt_i32_e32 vcc, v206, v85
	v_add_u32_e32 v207, 51, v178
	v_mul_f32_e32 v201, v97, v200
	v_cndmask_b32_e32 v168, 0, v99, vcc
	v_mul_f32_e32 v99, v165, v99
	v_add_f32_e32 v165, 1.0, v167
	v_rcp_f32_e32 v165, v165
	v_cndmask_b32_e32 v99, 1.0, v99, vcc
	v_cmp_lt_i32_e32 vcc, v207, v85
	v_mul_f32_e32 v97, v96, v201
	ds_bpermute_b32 v163, v252, v97
	v_cndmask_b32_e32 v218, 0, v165, vcc
	v_mul_f32_e32 v165, v167, v165
	v_cndmask_b32_e32 v170, 1.0, v165, vcc
	v_mul_f32_e32 v219, v170, v99
	ds_bpermute_b32 v96, v253, v97
	v_mul_f32_e32 v220, v95, v219
	ds_bpermute_b32 v166, v254, v97
	v_mul_f32_e32 v172, v76, v220
	ds_bpermute_b32 v173, v253, v172
	ds_bpermute_b32 v174, v252, v172
	ds_bpermute_b32 v175, v254, v172
	v_mul_f32_e32 v162, v64, v72
	s_waitcnt lgkmcnt(5)
	v_cndmask_b32_e64 v64, 1.0, v163, s[14:15]
	s_waitcnt lgkmcnt(4)
	v_cndmask_b32_e64 v72, 1.0, v96, s[16:17]
	v_mul_f32_e32 v64, v64, v72
	s_waitcnt lgkmcnt(3)
	v_cndmask_b32_e64 v72, 1.0, v166, s[18:19]
	v_mul_f32_e32 v99, v72, v64
	s_waitcnt lgkmcnt(2)
	v_cndmask_b32_e64 v64, 1.0, v173, s[16:17]
	s_waitcnt lgkmcnt(0)
	v_pk_mul_f32 v[172:173], v[172:173], v[174:175]
	v_mul_f32_e32 v176, v97, v163
	v_mov_b32_e32 v97, v172
	v_mov_b32_e32 v167, v173
	v_pk_mul_f32 v[96:97], v[96:97], v[166:167]
	v_mov_b32_e32 v177, v91
	v_pk_mul_f32 v[166:167], v[176:177], v[96:97]
	v_cndmask_b32_e64 v72, 1.0, v174, s[14:15]
	v_mov_b32_e32 v163, v166
	v_mov_b32_e32 v165, v167
	v_pk_mul_f32 v[96:97], v[162:163], v[164:165]
	v_mul_f32_e32 v64, v72, v64
	v_cndmask_b32_e64 v72, 1.0, v175, s[18:19]
	v_mov_b32_e32 v95, v97
	v_mul_f32_e32 v171, v72, v64
	v_mul_f32_e32 v64, v70, v66
	v_pk_mul_f32 v[92:93], v[92:93], v[94:95]
	v_mul_f32_e32 v66, v74, v68
	v_mul_f32_e32 v95, v64, v93
	v_mul_f32_e32 v64, v101, v201
	v_mov_b32_e32 v101, v167
	v_mul_f32_e32 v163, v66, v93
	v_mul_f32_e32 v165, v92, v93
	v_mul_f32_e32 v176, v78, v93
	v_mul_f32_e32 v66, v169, v200
	v_pk_mul_f32 v[92:93], v[98:99], v[100:101]
	v_mov_b32_e32 v169, v91
	v_min_f32_e32 v78, 0x42e6d4ca, v141
	v_mul_f32_e32 v99, v64, v93
	v_mul_f32_e32 v101, v66, v93
	v_mul_f32_e32 v200, v92, v93
	v_mul_f32_e32 v199, v199, v93
	v_pk_mul_f32 v[92:93], v[168:169], v[170:171]
	v_mul_f32_e32 v66, v205, v219
	v_mul_f32_e32 v205, v92, v93
	v_exp_f32_e32 v92, v78
	v_min_f32_e32 v98, 0x42e6d4ca, v140
	v_exp_f32_e32 v98, v98
	v_add_f32_e32 v94, 1.0, v92
	v_rcp_f32_e32 v94, v94
	v_mul_f32_e32 v64, v203, v220
	v_cmp_lt_i32_e32 vcc, v180, v88
	v_mul_f32_e32 v201, v64, v93
	v_mul_f32_e32 v203, v66, v93
	v_mul_f32_e32 v93, v218, v93
	v_cndmask_b32_e32 v218, 0, v94, vcc
	v_mul_f32_e32 v92, v92, v94
	v_min_f32_e32 v94, 0x42e6d4ca, v139
	v_cndmask_b32_e32 v100, 1.0, v92, vcc
	v_add_f32_e32 v92, 1.0, v98
	v_min_f32_e32 v162, 0x42e6d4ca, v138
	v_rcp_f32_e32 v92, v92
	v_exp_f32_e32 v94, v94
	v_exp_f32_e32 v162, v162
	v_cmp_lt_i32_e32 vcc, v181, v88
	v_min_f32_e32 v64, 0x42e6d4ca, v145
	s_nop 0
	v_cndmask_b32_e32 v219, 0, v92, vcc
	v_mul_f32_e32 v92, v98, v92
	v_add_f32_e32 v98, 1.0, v94
	v_rcp_f32_e32 v98, v98
	v_add_f32_e32 v166, 1.0, v162
	v_rcp_f32_e32 v166, v166
	v_cndmask_b32_e32 v164, 1.0, v92, vcc
	v_cmp_lt_i32_e32 vcc, v182, v88
	v_mul_f32_e32 v94, v94, v98
	v_min_f32_e32 v66, 0x42e6d4ca, v144
	v_cndmask_b32_e32 v92, 0, v98, vcc
	v_cndmask_b32_e32 v98, 1.0, v94, vcc
	v_mul_f32_e32 v94, v162, v166
	v_min_f32_e32 v162, 0x42e6d4ca, v137
	v_cmp_lt_i32_e32 vcc, v183, v88
	v_exp_f32_e32 v162, v162
	v_exp_f32_e32 v68, v64
	v_cndmask_b32_e32 v94, 1.0, v94, vcc
	v_mul_f32_e32 v221, v94, v98
	v_mul_f32_e32 v222, v164, v221
	v_mul_f32_e32 v183, v100, v222
	v_add_f32_e32 v98, 1.0, v162
	v_min_f32_e32 v100, 0x42e6d4ca, v136
	v_rcp_f32_e32 v98, v98
	v_exp_f32_e32 v100, v100
	v_cndmask_b32_e32 v220, 0, v166, vcc
	v_cmp_lt_i32_e32 vcc, v184, v88
; __device__ __forceinline__ float fexp(float x) { return __builtin_amdgcn_exp2f(x * 1.44269504f); }
; __device__ __forceinline__ unsigned pack2(float a, float b) { unsigned r; asm volatile("v_cvt_pk_bf16_f32 %0, %1, %2" : "=v"(r) : "v"(a), "v"(b)); return r; }
; __device__ __forceinline__ void item_attn(const Params& p, int l, int aidx) {
;     ...
; #pragma unroll
;           for (int m = 0; m < 4; ++m) {
;             float f[4];
; #pragma unroll
;             for (int j = 0; j < 4; ++j) {
;               const float e = fexp(fminf(-z[m][n][j], 80.f));
;               const float sg = __builtin_amdgcn_rcpf(1.f + e);
;               if (decltype(MASKED)::value) {
;                 const bool ok = (kt * 64 + m * 16 + fq * 4 + j) < qpos;
;                 wgt[m][j] = ok ? sg : 0.f;
;                 f[j] = ok ? e * sg : 1.f;
;               } else { wgt[m][j] = sg; f[j] = e * sg; }
;             }
;             excl[m][3] = 1.f; excl[m][2] = f[3]; excl[m][1] = f[3] * f[2]; excl[m][0] = excl[m][1] * f[1];
;             const float G = excl[m][0] * f[0];
;             const float g1 = __shfl_xor(G, 16), g2 = __shfl_xor(G, 32), g3 = __shfl_xor(G, 48);
;             later[m] = ((fq ^ 1) > fq ? g1 : 1.f) * ((fq ^ 2) > fq ? g2 : 1.f) * ((fq ^ 3) > fq ? g3 : 1.f);
;             TT[m] = (G * g1) * (g2 * g3);
;           }
;           float lm[4]; lm[3] = carry[n]; lm[2] = lm[3] * TT[3]; lm[1] = lm[2] * TT[2]; lm[0] = lm[1] * TT[1];
; #pragma unroll
;           for (int m = 0; m < 4; ++m) {
;             const float base = later[m] * lm[m];
;             float pv[4];
; #pragma unroll
;             for (int j = 0; j < 4; ++j) pv[j] = wgt[m][j] * excl[m][j] * base;
;             pk[m][n][0] = pack2(pv[0], pv[1]); pk[m][n][1] = pack2(pv[2], pv[3]);
;           }
;           carry[n] = lm[0] * TT[0];
	v_min_f32_e32 v164, 0x42e6d4ca, v135
	s_nop 0
	v_cndmask_b32_e32 v184, 0, v98, vcc
	v_mul_f32_e32 v98, v162, v98
	v_cndmask_b32_e32 v162, 1.0, v98, vcc
	v_add_f32_e32 v98, 1.0, v100
	v_min_f32_e32 v166, 0x42e6d4ca, v134
	v_rcp_f32_e32 v98, v98
	v_exp_f32_e32 v164, v164
	v_exp_f32_e32 v166, v166
	v_cmp_lt_i32_e32 vcc, v185, v88
	v_exp_f32_e32 v66, v66
	s_nop 0
	v_cndmask_b32_e32 v185, 0, v98, vcc
	v_mul_f32_e32 v98, v100, v98
	v_add_f32_e32 v100, 1.0, v164
	v_rcp_f32_e32 v100, v100
	v_add_f32_e32 v168, 1.0, v166
	v_rcp_f32_e32 v168, v168
	v_cndmask_b32_e32 v167, 1.0, v98, vcc
	v_cmp_lt_i32_e32 vcc, v186, v88
	v_add_f32_e32 v64, 1.0, v68
	v_min_f32_e32 v70, 0x42e6d4ca, v142
	v_cndmask_b32_e32 v98, 0, v100, vcc
	v_mul_f32_e32 v100, v164, v100
	v_cndmask_b32_e32 v164, 1.0, v100, vcc
	v_mul_f32_e32 v100, v166, v168
	v_min_f32_e32 v166, 0x42e6d4ca, v132
	v_cmp_lt_i32_e32 vcc, v187, v88
	v_exp_f32_e32 v166, v166
	v_rcp_f32_e32 v72, v64
	v_cndmask_b32_e32 v100, 1.0, v100, vcc
	v_mul_f32_e32 v187, v100, v164
	v_mul_f32_e32 v223, v167, v187
	v_mul_f32_e32 v224, v162, v223
	v_add_f32_e32 v162, 1.0, v166
	v_min_f32_e32 v164, 0x42e6d4ca, v133
	v_rcp_f32_e32 v162, v162
	v_exp_f32_e32 v164, v164
	v_cndmask_b32_e32 v186, 0, v168, vcc
	v_cmp_lt_i32_e32 vcc, v202, v88
	v_add_f32_e32 v64, 1.0, v66
	v_min_f32_e32 v168, 0x42e6d4ca, v130
	v_cndmask_b32_e32 v202, 0, v162, vcc
	v_mul_f32_e32 v162, v166, v162
	v_min_f32_e32 v166, 0x42e6d4ca, v131
	v_cndmask_b32_e32 v167, 1.0, v162, vcc
	v_add_f32_e32 v162, 1.0, v164
	v_rcp_f32_e32 v162, v162
	v_exp_f32_e32 v166, v166
	v_rcp_f32_e32 v74, v64
	v_min_f32_e32 v64, 0x42e6d4ca, v143
	v_exp_f32_e32 v70, v70
	v_exp_f32_e32 v168, v168
	v_exp_f32_e32 v64, v64
	v_cmp_lt_i32_e32 vcc, v204, v88
	v_add_f32_e32 v76, 1.0, v70
	v_add_f32_e32 v169, 1.0, v168
	v_cndmask_b32_e32 v204, 0, v162, vcc
	v_mul_f32_e32 v162, v164, v162
	v_add_f32_e32 v164, 1.0, v166
	v_rcp_f32_e32 v164, v164
	v_add_f32_e32 v79, 1.0, v71
	v_rcp_f32_e32 v78, v76
	v_add_f32_e32 v76, 1.0, v64
	v_rcp_f32_e32 v169, v169
	v_rcp_f32_e32 v79, v79
	v_rcp_f32_e32 v76, v76
	v_cndmask_b32_e32 v180, 1.0, v162, vcc
	v_cmp_lt_i32_e32 vcc, v206, v88
	v_add_u32_e32 v179, 1, v178
	v_pk_mul_f32 v[70:71], v[70:71], v[78:79]
	v_cndmask_b32_e32 v162, 0, v164, vcc
	v_mul_f32_e32 v164, v166, v164
	v_cndmask_b32_e32 v166, 1.0, v164, vcc
	v_cmp_lt_i32_e32 vcc, v207, v88
	v_mul_f32_e32 v164, v168, v169
	v_or_b32_e32 v168, 3, v178
	v_cndmask_b32_e32 v206, 0, v169, vcc
	v_or_b32_e32 v169, 2, v178
	v_cndmask_b32_e32 v164, 1.0, v164, vcc
	v_cmp_lt_i32_e64 s[24:25], v169, v85
	v_cmp_lt_i32_e64 s[26:27], v168, v85
	v_pk_mul_f32 v[64:65], v[64:65], v[76:77]
	v_mul_f32_e32 v207, v164, v166
	v_cmp_lt_i32_e64 s[22:23], v179, v85
	v_cndmask_b32_e64 v166, 0, v77, s[24:25]
	v_cndmask_b32_e64 v227, 0, v79, s[26:27]
	v_pk_mul_f32 v[66:67], v[66:67], v[74:75]
	v_cndmask_b32_e64 v71, 1.0, v71, s[26:27]
	v_cmp_lt_i32_e64 s[26:27], v169, v88
	v_cndmask_b32_e64 v169, 1.0, v65, s[24:25]
	v_cmp_lt_i32_e64 s[24:25], v168, v88
	v_cmp_lt_i32_e32 vcc, v178, v85
	v_cndmask_b32_e64 v226, 0, v75, s[22:23]
	v_pk_mul_f32 v[68:69], v[68:69], v[72:73]
	v_cndmask_b32_e64 v67, 1.0, v67, s[22:23]
	v_cmp_lt_i32_e64 s[22:23], v179, v88
	v_cndmask_b32_e64 v70, 1.0, v70, s[26:27]
	v_cndmask_b32_e64 v168, 1.0, v64, s[24:25]
	v_cndmask_b32_e32 v225, 0, v73, vcc
	v_cndmask_b32_e32 v69, 1.0, v69, vcc
	v_cmp_lt_i32_e32 vcc, v178, v88
	v_cndmask_b32_e64 v66, 1.0, v66, s[22:23]
	v_pk_mul_f32 v[170:171], v[70:71], v[168:169]
	v_cndmask_b32_e32 v68, 1.0, v68, vcc
	v_pk_mul_f32 v[172:173], v[66:67], v[170:171]
	v_mul_f32_e32 v228, v180, v207
	v_pk_mul_f32 v[174:175], v[68:69], v[172:173]
	ds_bpermute_b32 v177, v252, v175
	ds_bpermute_b32 v179, v253, v175
	ds_bpermute_b32 v181, v254, v175
	v_pk_mul_f32 v[96:97], v[96:97], v[96:97] op_sel:[0,1] op_sel_hi:[1,0]
	v_mul_f32_e32 v182, v167, v228
	s_waitcnt lgkmcnt(2)
	v_cndmask_b32_e64 v64, 1.0, v177, s[14:15]
	s_waitcnt lgkmcnt(1)
	v_cndmask_b32_e64 v65, 1.0, v179, s[16:17]
	v_mul_f32_e32 v64, v64, v65
	s_waitcnt lgkmcnt(0)
; __device__ __forceinline__ unsigned pack2(float a, float b) { unsigned r; asm volatile("v_cvt_pk_bf16_f32 %0, %1, %2" : "=v"(r) : "v"(a), "v"(b)); return r; }
; __device__ __forceinline__ void item_attn(const Params& p, int l, int aidx) {
;     ...
;             excl[m][3] = 1.f; excl[m][2] = f[3]; excl[m][1] = f[3] * f[2]; excl[m][0] = excl[m][1] * f[1];
;             const float G = excl[m][0] * f[0];
;             const float g1 = __shfl_xor(G, 16), g2 = __shfl_xor(G, 32), g3 = __shfl_xor(G, 48);
;             later[m] = ((fq ^ 1) > fq ? g1 : 1.f) * ((fq ^ 2) > fq ? g2 : 1.f) * ((fq ^ 3) > fq ? g3 : 1.f);
;             TT[m] = (G * g1) * (g2 * g3);
;           }
;           float lm[4]; lm[3] = carry[n]; lm[2] = lm[3] * TT[3]; lm[1] = lm[2] * TT[2]; lm[0] = lm[1] * TT[1];
; #pragma unroll
;           for (int m = 0; m < 4; ++m) {
;             const float base = later[m] * lm[m];
;             float pv[4];
; #pragma unroll
;             for (int j = 0; j < 4; ++j) pv[j] = wgt[m][j] * excl[m][j] * base;
;             pk[m][n][0] = pack2(pv[0], pv[1]); pk[m][n][1] = pack2(pv[2], pv[3]);
;           }
;           carry[n] = lm[0] * TT[0];
;         }
;       };
;       if (kt * 64 + 63 < qpos0 + 32 * wid) sb_weights(std::false_type{}); else sb_weights(std::true_type{});
	v_cndmask_b32_e64 v65, 1.0, v181, s[18:19]
	v_mul_f32_e32 v167, v65, v64
	v_pk_mov_b32 v[64:65], v[70:71], v[96:97] op_sel:[1,0]
	v_mul_f32_e32 v66, v225, v173
	v_mul_f32_e32 v67, v226, v171
	v_pk_mul_f32 v[64:65], v[166:167], v[64:65]
	ds_bpermute_b32 v178, v253, v174
	v_mul_f32_e32 v66, v66, v65
	v_mul_f32_e32 v67, v67, v65
	v_mul_f32_e32 v64, v64, v65
	v_mul_f32_e32 v65, v227, v65
	v_cvt_pk_bf16_f32 v68, v66, v67
	v_cvt_pk_bf16_f32 v69, v64, v65
	v_cvt_pk_bf16_f32 v70, v95, v163
	v_cvt_pk_bf16_f32 v71, v165, v176
	ds_bpermute_b32 v176, v252, v174
	ds_bpermute_b32 v180, v254, v174
	ds_bpermute_b32 v75, v252, v183
	ds_bpermute_b32 v77, v253, v183
	ds_bpermute_b32 v79, v254, v183
	v_cndmask_b32_e64 v97, 0, v74, s[22:23]
	s_waitcnt lgkmcnt(4)
	v_cndmask_b32_e64 v73, 1.0, v176, s[14:15]
	v_cndmask_b32_e64 v74, 1.0, v178, s[16:17]
	v_mul_f32_e32 v73, v73, v74
	s_waitcnt lgkmcnt(3)
	v_cndmask_b32_e64 v74, 1.0, v180, s[18:19]
	v_cvt_pk_bf16_f32 v64, v99, v101
	v_cndmask_b32_e64 v101, 0, v76, s[24:25]
	v_mul_f32_e32 v73, v74, v73
	s_waitcnt lgkmcnt(2)
	v_cndmask_b32_e64 v74, 1.0, v75, s[14:15]
	s_waitcnt lgkmcnt(1)
	v_cndmask_b32_e64 v76, 1.0, v77, s[16:17]
	v_mul_f32_e32 v74, v74, v76
	s_waitcnt lgkmcnt(0)
	v_cndmask_b32_e64 v76, 1.0, v79, s[18:19]
	v_cvt_pk_bf16_f32 v65, v200, v199
	v_cvt_pk_bf16_f32 v66, v201, v203
	v_cvt_pk_bf16_f32 v67, v205, v93
	v_mul_f32_e32 v93, v76, v74
	ds_bpermute_b32 v163, v252, v224
	ds_bpermute_b32 v74, v253, v224
	v_cndmask_b32_e32 v95, 0, v72, vcc
	v_cndmask_b32_e64 v72, 0, v78, s[26:27]
	ds_bpermute_b32 v78, v254, v224
	v_pk_mul_f32 v[166:167], v[174:175], v[176:177]
	v_mul_f32_e32 v76, v183, v75
	ds_bpermute_b32 v183, v253, v182
	ds_bpermute_b32 v176, v252, v182
	ds_bpermute_b32 v177, v254, v182
	v_pk_mul_f32 v[174:175], v[178:179], v[180:181]
	s_waitcnt lgkmcnt(5)
	v_cndmask_b32_e64 v75, 1.0, v163, s[14:15]
	v_pk_mul_f32 v[166:167], v[166:167], v[174:175]
	v_mul_f32_e32 v174, v77, v79
	s_waitcnt lgkmcnt(4)
	v_cndmask_b32_e64 v77, 1.0, v74, s[16:17]
	v_mul_f32_e32 v75, v75, v77
	s_waitcnt lgkmcnt(3)
	v_cndmask_b32_e64 v77, 1.0, v78, s[18:19]
	v_mul_f32_e32 v99, v77, v75
	s_waitcnt lgkmcnt(2)
	v_cndmask_b32_e64 v75, 1.0, v183, s[16:17]
	s_waitcnt lgkmcnt(1)
	v_cndmask_b32_e64 v77, 1.0, v176, s[14:15]
	v_mul_f32_e32 v75, v77, v75
	s_waitcnt lgkmcnt(0)
	v_cndmask_b32_e64 v77, 1.0, v177, s[18:19]
	v_pk_mul_f32 v[176:177], v[182:183], v[176:177]
	v_mul_f32_e32 v165, v77, v75
	v_mov_b32_e32 v75, v176
	v_mov_b32_e32 v79, v177
	v_mul_f32_e32 v178, v224, v163
	v_pk_mul_f32 v[74:75], v[74:75], v[78:79]
	v_mov_b32_e32 v179, v90
	v_pk_mul_f32 v[78:79], v[178:179], v[74:75]
	v_mov_b32_e32 v163, v90
	v_mov_b32_e32 v77, v78
	v_mov_b32_e32 v175, v79
	v_pk_mul_f32 v[74:75], v[76:77], v[174:175]
	v_mul_f32_e32 v76, v97, v170
	v_pk_mul_f32 v[174:175], v[74:75], v[74:75] op_sel:[0,1] op_sel_hi:[1,0]
	v_mul_f32_e32 v74, v95, v172
	v_mov_b32_e32 v169, v174
	v_pk_mul_f32 v[72:73], v[72:73], v[168:169]
	v_mov_b32_e32 v95, v75
	v_mul_f32_e32 v74, v74, v73
	v_mul_f32_e32 v76, v76, v73
	v_mul_f32_e32 v77, v72, v73
	v_mul_f32_e32 v73, v101, v73
	v_cvt_pk_bf16_f32 v72, v74, v76
	v_cvt_pk_bf16_f32 v73, v77, v73
	v_mul_f32_e32 v76, v218, v222
	v_mul_f32_e32 v77, v219, v221
	v_pk_mul_f32 v[74:75], v[92:93], v[94:95]
	v_mov_b32_e32 v101, v79
	v_mul_f32_e32 v76, v76, v75
	v_mul_f32_e32 v77, v77, v75
	v_mul_f32_e32 v78, v74, v75
	v_mul_f32_e32 v75, v220, v75
	v_cvt_pk_bf16_f32 v74, v76, v77
	v_cvt_pk_bf16_f32 v75, v78, v75
	v_mul_f32_e32 v78, v184, v223
	v_mul_f32_e32 v92, v185, v187
	v_pk_mul_f32 v[76:77], v[98:99], v[100:101]
	v_mul_f32_e32 v93, v204, v207
	v_mul_f32_e32 v78, v78, v77
	v_mul_f32_e32 v79, v92, v77
	v_mul_f32_e32 v92, v76, v77
	v_mul_f32_e32 v77, v186, v77
	v_cvt_pk_bf16_f32 v76, v78, v79
	v_cvt_pk_bf16_f32 v77, v92, v77
	v_mul_f32_e32 v92, v202, v228
	v_pk_mul_f32 v[78:79], v[162:163], v[164:165]
	v_mov_b32_e32 v175, v96
	v_mul_f32_e32 v92, v92, v79
	v_mul_f32_e32 v93, v93, v79
	v_mul_f32_e32 v94, v78, v79
	v_mul_f32_e32 v79, v206, v79
	v_cvt_pk_bf16_f32 v78, v92, v93
	v_pk_mul_f32 v[92:93], v[166:167], v[174:175]
	s_mov_b64 s[0:1], 0
	v_cvt_pk_bf16_f32 v79, v94, v79

; __device__ __forceinline__ unsigned pack2(float a, float b) { unsigned r; asm volatile("v_cvt_pk_bf16_f32 %0, %1, %2" : "=v"(r) : "v"(a), "v"(b)); return r; }
; __device__ __forceinline__ void item_attn(const Params& p, int l, int aidx) {
;     ...
;   {
;     uint2 gz[2][4];
; #pragma unroll
;     for (int n = 0; n < 2; ++n) {
;       int row = 32 * wid + 16 * n + fr; if (row >= nq) row = nq - 1;
; #pragma unroll
;       for (int md = 0; md < 4; ++md) gz[n][md] = *reinterpret_cast<const uint2*>(p.gzc + (tokq0 + row) * 512 + hd * 64 + md * 16 + fq * 4);
;     }
; #pragma unroll
;     for (int n = 0; n < 2; ++n) {
;       const int row = 32 * wid + 16 * n + fr;
; #pragma unroll
;       for (int md = 0; md < 4; ++md) {
;         const uint2 g2 = gz[n][md];
;         float g0 = __uint_as_float(g2.x << 16), g1 = __uint_as_float(g2.x & 0xffff0000u);
;         float g2f = __uint_as_float(g2.y << 16), g3 = __uint_as_float(g2.y & 0xffff0000u);
;         uint2 o2; o2.x = pack2(oacc[md][n][0] * g0, oacc[md][n][1] * g1); o2.y = pack2(oacc[md][n][2] * g2f, oacc[md][n][3] * g3);
;         if (row < nq) *reinterpret_cast<uint2*>(p.sq + (tokq0 + row) * 512 + hd * 64 + md * 16 + fq * 4) = o2;
;       }
;     }
;   }
.LBB0_773:
	s_waitcnt vmcnt(0)
	s_add_i32 s2, s47, -1
	v_readlane_b32 s12, v247, 7
	v_readlane_b32 s18, v247, 13
	v_min_i32_e32 v2, s2, v84
	v_readlane_b32 s19, v247, 14
	s_add_u32 s0, s18, s44
	v_ashrrev_i32_e32 v3, 31, v2
	s_addc_u32 s1, s19, s45
	v_lshlrev_b32_e32 v190, 1, v114
	v_lshl_add_u64 v[2:3], s[34:35], 0, v[2:3]
	v_lshl_add_u64 v[0:1], s[0:1], 0, v[190:191]
	v_lshlrev_b64 v[2:3], 10, v[2:3]
	v_lshl_add_u64 v[2:3], v[0:1], 0, v[2:3]
	v_mov_b32_e32 v10, v230
	v_mov_b32_e32 v11, v231
	v_mov_b32_e32 v14, v232
	v_mov_b32_e32 v15, v233
	v_mov_b32_e32 v12, v234
	v_mov_b32_e32 v13, v235
	v_mov_b32_e32 v8, v236
	v_mov_b32_e32 v9, v237
	v_min_i32_e32 v2, s2, v86
	v_ashrrev_i32_e32 v3, 31, v2
	v_lshl_add_u64 v[2:3], s[34:35], 0, v[2:3]
	v_lshlrev_b64 v[2:3], 10, v[2:3]
	v_lshl_add_u64 v[0:1], v[0:1], 0, v[2:3]
	v_mov_b32_e32 v6, v238
	v_mov_b32_e32 v7, v239
	v_mov_b32_e32 v4, v240
	v_mov_b32_e32 v5, v241
	v_mov_b32_e32 v2, v242
	v_mov_b32_e32 v3, v243
	s_nop 0
	v_mov_b32_e32 v0, v229
	v_mov_b32_e32 v1, v244
	v_readlane_b32 s16, v247, 11
	v_readlane_b32 s17, v247, 12
	v_readlane_b32 s13, v247, 8
	v_readlane_b32 s14, v247, 9
	v_lshl_add_u64 v[18:19], s[16:17], 0, v[82:83]
	v_readlane_b32 s15, v247, 10
	v_readlane_b32 s20, v247, 15
	v_readlane_b32 s21, v247, 16
	v_readlane_b32 s22, v247, 17
	v_readlane_b32 s23, v247, 18
	v_readlane_b32 s24, v247, 19
	v_readlane_b32 s25, v247, 20
	v_readlane_b32 s26, v247, 21
	v_readlane_b32 s27, v247, 22
	v_lshlrev_b32_e32 v16, 16, v10
	v_and_b32_e32 v10, 0xffff0000, v10
	v_lshlrev_b32_e32 v17, 16, v11
	v_and_b32_e32 v11, 0xffff0000, v11
	v_mul_f32_e32 v16, v60, v16
	v_mul_f32_e32 v10, v61, v10
	v_mul_f32_e32 v17, v62, v17
	v_mul_f32_e32 v11, v63, v11
	v_cvt_pk_bf16_f32 v16, v16, v10
	v_cvt_pk_bf16_f32 v17, v17, v11
	v_lshl_add_u64 v[10:11], s[28:29], 1, v[18:19]
	s_and_saveexec_b64 s[0:1], s[8:9]
	s_cbranch_execz .LBB0_775
	v_lshl_add_u64 v[18:19], v[10:11], 0, v[190:191]
	global_store_dwordx2 v[18:19], v[16:17], off
.LBB0_775:
	s_or_b64 exec, exec, s[0:1]
	v_lshlrev_b32_e32 v16, 16, v14
	v_and_b32_e32 v14, 0xffff0000, v14
	v_lshlrev_b32_e32 v17, 16, v15
	v_and_b32_e32 v15, 0xffff0000, v15
	v_mul_f32_e32 v16, v56, v16
	v_mul_f32_e32 v14, v57, v14
	v_mul_f32_e32 v15, v59, v15
	v_cvt_pk_bf16_f32 v14, v16, v14
	v_mul_f32_e32 v16, v58, v17
	v_cvt_pk_bf16_f32 v15, v16, v15
	s_and_saveexec_b64 s[0:1], s[8:9]
	v_readlane_b32 s44, v246, 29
	v_readlane_b32 s24, v246, 31
	v_readlane_b32 s45, v246, 30
	v_readlane_b32 s25, v246, 32
	s_cbranch_execz .LBB0_777
	v_lshl_add_u64 v[16:17], v[10:11], 0, v[190:191]
	global_store_dwordx2 v[16:17], v[14:15], off offset:32
.LBB0_777:
	s_or_b64 exec, exec, s[0:1]
	v_lshlrev_b32_e32 v14, 16, v12
	v_and_b32_e32 v12, 0xffff0000, v12
	v_lshlrev_b32_e32 v15, 16, v13
	v_and_b32_e32 v13, 0xffff0000, v13
	v_mul_f32_e32 v14, v52, v14
	v_mul_f32_e32 v12, v53, v12
	v_mul_f32_e32 v13, v55, v13
	v_cvt_pk_bf16_f32 v12, v14, v12
	v_mul_f32_e32 v14, v54, v15
	v_cvt_pk_bf16_f32 v13, v14, v13
	s_and_saveexec_b64 s[0:1], s[8:9]
	s_cbranch_execz .LBB0_779
	v_lshl_add_u64 v[14:15], v[10:11], 0, v[190:191]
	global_store_dwordx2 v[14:15], v[12:13], off offset:64
.LBB0_779:
	s_or_b64 exec, exec, s[0:1]
	v_lshlrev_b32_e32 v12, 16, v8
	v_and_b32_e32 v8, 0xffff0000, v8
	v_lshlrev_b32_e32 v13, 16, v9
	v_and_b32_e32 v9, 0xffff0000, v9
	v_mul_f32_e32 v12, v48, v12
	v_mul_f32_e32 v8, v49, v8
	v_mul_f32_e32 v9, v51, v9
	v_cvt_pk_bf16_f32 v8, v12, v8
	v_mul_f32_e32 v12, v50, v13
	v_cvt_pk_bf16_f32 v9, v12, v9
	s_and_saveexec_b64 s[0:1], s[8:9]
	s_cbranch_execz .LBB0_781
	v_lshl_add_u64 v[10:11], v[10:11], 0, v[190:191]
	global_store_dwordx2 v[10:11], v[8:9], off offset:96
.LBB0_781:
	s_or_b64 exec, exec, s[0:1]
	v_lshlrev_b32_e32 v8, 16, v6
	v_and_b32_e32 v6, 0xffff0000, v6
	v_lshlrev_b32_e32 v9, 16, v7
	v_and_b32_e32 v7, 0xffff0000, v7
	v_mul_f32_e32 v8, v44, v8
	v_mul_f32_e32 v6, v45, v6
	v_readlane_b32 s8, v247, 7
	v_cvt_pk_bf16_f32 v8, v8, v6
	v_mul_f32_e32 v6, v46, v9
	v_mul_f32_e32 v7, v47, v7
	v_readlane_b32 s12, v247, 11
	v_readlane_b32 s13, v247, 12
	v_cvt_pk_bf16_f32 v9, v6, v7
	v_readlane_b32 s9, v247, 8
	v_readlane_b32 s10, v247, 9
	v_lshl_add_u64 v[6:7], s[12:13], 0, v[80:81]
	v_lshl_add_u64 v[6:7], s[28:29], 1, v[6:7]
	v_readlane_b32 s11, v247, 10
	v_readlane_b32 s14, v247, 13
	v_readlane_b32 s15, v247, 14
	v_readlane_b32 s16, v247, 15
	v_readlane_b32 s17, v247, 16
	v_readlane_b32 s18, v247, 17
	v_readlane_b32 s19, v247, 18
	v_readlane_b32 s20, v247, 19
	v_readlane_b32 s21, v247, 20
	v_readlane_b32 s22, v247, 21
	v_readlane_b32 s23, v247, 22
	s_and_saveexec_b64 s[0:1], s[6:7]
	s_cbranch_execz .LBB0_783
	v_lshl_add_u64 v[10:11], v[6:7], 0, v[190:191]
	global_store_dwordx2 v[10:11], v[8:9], off
.LBB0_783:
	s_or_b64 exec, exec, s[0:1]
	v_lshlrev_b32_e32 v8, 16, v4
	v_and_b32_e32 v4, 0xffff0000, v4
	v_lshlrev_b32_e32 v9, 16, v5
	v_and_b32_e32 v5, 0xffff0000, v5
	v_mul_f32_e32 v8, v36, v8
	v_mul_f32_e32 v4, v37, v4
	v_mul_f32_e32 v5, v39, v5
	v_cvt_pk_bf16_f32 v4, v8, v4
	v_mul_f32_e32 v8, v38, v9
	v_cvt_pk_bf16_f32 v5, v8, v5
	s_and_saveexec_b64 s[0:1], s[6:7]
	s_cbranch_execz .LBB0_785
	v_lshl_add_u64 v[8:9], v[6:7], 0, v[190:191]
	global_store_dwordx2 v[8:9], v[4:5], off offset:32
.LBB0_785:
	s_or_b64 exec, exec, s[0:1]
	v_lshlrev_b32_e32 v4, 16, v2
	v_and_b32_e32 v2, 0xffff0000, v2
	v_lshlrev_b32_e32 v5, 16, v3
	v_and_b32_e32 v3, 0xffff0000, v3
	v_mul_f32_e32 v4, v40, v4
	v_mul_f32_e32 v2, v41, v2
	v_mul_f32_e32 v3, v43, v3
	v_cvt_pk_bf16_f32 v2, v4, v2
	v_mul_f32_e32 v4, v42, v5
	v_cvt_pk_bf16_f32 v3, v4, v3
	s_and_saveexec_b64 s[0:1], s[6:7]
	s_cbranch_execz .LBB0_787
	v_lshl_add_u64 v[4:5], v[6:7], 0, v[190:191]
	global_store_dwordx2 v[4:5], v[2:3], off offset:64
.LBB0_787:
	s_or_b64 exec, exec, s[0:1]
	v_lshlrev_b32_e32 v2, 16, v0
	v_and_b32_e32 v0, 0xffff0000, v0
	v_lshlrev_b32_e32 v3, 16, v1
	v_and_b32_e32 v1, 0xffff0000, v1
	v_mul_f32_e32 v2, v32, v2
	v_mul_f32_e32 v0, v33, v0
	v_mul_f32_e32 v1, v35, v1
	v_cvt_pk_bf16_f32 v0, v2, v0
	v_mul_f32_e32 v2, v34, v3
	v_cvt_pk_bf16_f32 v1, v2, v1
	s_and_saveexec_b64 s[0:1], s[6:7]
	s_cbranch_execz .LBB0_789
	v_lshl_add_u64 v[2:3], v[6:7], 0, v[190:191]
	global_store_dwordx2 v[2:3], v[0:1], off offset:96

; __device__ __forceinline__ unsigned xb_add(unsigned* p, unsigned v) { return __hip_atomic_fetch_add(p, v, __ATOMIC_RELAXED, __HIP_MEMORY_SCOPE_AGENT); }
; __device__ __forceinline__ unsigned xb_xcc_id() { return (unsigned)__builtin_amdgcn_s_getreg((3 << 11) | 20) & 0xFu; }
; __global__ void __launch_bounds__(NTHR) fwd_mega(Params p, int ph_lo, int ph_hi) {
;   cg::grid_group grid = cg::this_grid();
;   if (threadIdx.x < 2) *reinterpret_cast<volatile unsigned*>(smem + LDS_BYTES - 32 + 4 * threadIdx.x) = 0u;
;   __syncthreads();
;   phase_prep(p);
;   phase_norm(p, 0);
;   grid.sync();
;   if (threadIdx.x == 0) (void)xb_add(&p.bar[XB_XCNT(xb_xcc_id())], 1u);
; #pragma unroll 1
;   for (int l = 0; l < 2; ++l) {
;     gemm_run(p, l, 1, -1);
;     grid_bar(p.bar);
;     phase_p2(p, l);
;     grid_bar(p.bar);
;     gemm_run(p, l, 3, -1);
;     grid_bar(p.bar);
;     gemm_run(p, l, 4, -1);
;     if (l == 0) {
;       grid_bar(p.bar);
;       phase_norm(p, 1);
;       grid_bar(p.bar);
;     }
;   }
; }
	.amdhsa_kernel _Z8fwd_mega6Paramsii
		.amdhsa_group_segment_fixed_size 256
		.amdhsa_private_segment_fixed_size 0
		.amdhsa_kernarg_size 536
		.amdhsa_user_sgpr_count 2
		.amdhsa_user_sgpr_dispatch_ptr 0
		.amdhsa_user_sgpr_queue_ptr 0
		.amdhsa_user_sgpr_kernarg_segment_ptr 1
		.amdhsa_user_sgpr_dispatch_id 0
		.amdhsa_user_sgpr_kernarg_preload_length 0
		.amdhsa_user_sgpr_kernarg_preload_offset 0
		.amdhsa_user_sgpr_private_segment_size 0
		.amdhsa_uses_dynamic_stack 0
		.amdhsa_enable_private_segment 0
		.amdhsa_system_sgpr_workgroup_id_x 1
		.amdhsa_system_sgpr_workgroup_id_y 0
		.amdhsa_system_sgpr_workgroup_id_z 0
		.amdhsa_system_sgpr_workgroup_info 0
		.amdhsa_system_vgpr_workitem_id 2
		.amdhsa_next_free_vgpr 256
		.amdhsa_next_free_sgpr 102
		.amdhsa_accum_offset 256
		.amdhsa_reserve_vcc 1
		.amdhsa_float_round_mode_32 0
		.amdhsa_float_round_mode_16_64 0
		.amdhsa_float_denorm_mode_32 3
		.amdhsa_float_denorm_mode_16_64 3
		.amdhsa_dx10_clamp 1
		.amdhsa_ieee_mode 1
		.amdhsa_fp16_overflow 0
		.amdhsa_tg_split 0
		.amdhsa_exception_fp_ieee_invalid_op 0
		.amdhsa_exception_fp_denorm_src 0
		.amdhsa_exception_fp_ieee_div_zero 0
		.amdhsa_exception_fp_ieee_overflow 0
		.amdhsa_exception_fp_ieee_underflow 0
		.amdhsa_exception_fp_ieee_inexact 0
		.amdhsa_exception_int_div_zero 0
	.end_amdhsa_kernel

; __device__ __forceinline__ unsigned xb_add(unsigned* p, unsigned v) { return __hip_atomic_fetch_add(p, v, __ATOMIC_RELAXED, __HIP_MEMORY_SCOPE_AGENT); }
; __device__ __forceinline__ unsigned xb_xcc_id() { return (unsigned)__builtin_amdgcn_s_getreg((3 << 11) | 20) & 0xFu; }
; __global__ void __launch_bounds__(NTHR) fwd_mega(Params p, int ph_lo, int ph_hi) {
;   cg::grid_group grid = cg::this_grid();
;   if (threadIdx.x < 2) *reinterpret_cast<volatile unsigned*>(smem + LDS_BYTES - 32 + 4 * threadIdx.x) = 0u;
;   __syncthreads();
;   phase_prep(p);
;   phase_norm(p, 0);
;   grid.sync();
;   if (threadIdx.x == 0) (void)xb_add(&p.bar[XB_XCNT(xb_xcc_id())], 1u);
; #pragma unroll 1
;   for (int l = 0; l < 2; ++l) {
;     gemm_run(p, l, 1, -1);
;     grid_bar(p.bar);
;     phase_p2(p, l);
;     grid_bar(p.bar);
;     gemm_run(p, l, 3, -1);
;     grid_bar(p.bar);
;     gemm_run(p, l, 4, -1);
;     if (l == 0) {
;       grid_bar(p.bar);
;       phase_norm(p, 1);
;       grid_bar(p.bar);
;     }
;   }
; }
amdhsa.kernels:
  - .agpr_count:     0
    .args:
      - .offset:         0
        .size:           272
        .value_kind:     by_value
      - .offset:         272
        .size:           4
        .value_kind:     by_value
      - .offset:         276
        .size:           4
        .value_kind:     by_value
      - .offset:         280
        .size:           4
        .value_kind:     hidden_block_count_x
      - .offset:         284
        .size:           4
        .value_kind:     hidden_block_count_y
      - .offset:         288
        .size:           4
        .value_kind:     hidden_block_count_z
      - .offset:         292
        .size:           2
        .value_kind:     hidden_group_size_x
      - .offset:         294
        .size:           2
        .value_kind:     hidden_group_size_y
      - .offset:         296
        .size:           2
        .value_kind:     hidden_group_size_z
      - .offset:         298
        .size:           2
        .value_kind:     hidden_remainder_x
      - .offset:         300
        .size:           2
        .value_kind:     hidden_remainder_y
      - .offset:         302
        .size:           2
        .value_kind:     hidden_remainder_z
      - .offset:         320
        .size:           8
        .value_kind:     hidden_global_offset_x
      - .offset:         328
        .size:           8
        .value_kind:     hidden_global_offset_y
      - .offset:         336
        .size:           8
        .value_kind:     hidden_global_offset_z
      - .offset:         344
        .size:           2
        .value_kind:     hidden_grid_dims
      - .offset:         368
        .size:           8
        .value_kind:     hidden_multigrid_sync_arg
      - .offset:         400
        .size:           4
        .value_kind:     hidden_dynamic_lds_size
    .group_segment_fixed_size: 256
    .kernarg_segment_align: 8
    .kernarg_segment_size: 536
    .language:       OpenCL C
    .language_version:
      - 2
      - 0
    .max_flat_workgroup_size: 512
    .name:           _Z8fwd_mega6Paramsii
    .private_segment_fixed_size: 0
    .sgpr_count:     108
    .sgpr_spill_count: 181
    .symbol:         _Z8fwd_mega6Paramsii.kd
    .uniform_work_group_size: 1
    .uses_dynamic_stack: false
    .vgpr_count:     256
    .vgpr_spill_count: 0
    .wavefront_size: 64
